# stack10 plus write-through sc0 sc1 on the mixer outputs (attention, pool, gmlp stores)
# baseline (speedup 1.0000x reference)
; #define MFMA32(a, b, c) __builtin_amdgcn_mfma_f32_32x32x16_bf16((a), (b), (c), 0, 0, 0)
; __device__ __forceinline__ void gmlp_unit(const bf16* GVT, const bf16* U, const float* wsp, const float* bsp, const float* gain, bf16* OGM, int unit, LAS unsigned char* lds, int tid, int wave, int lane) {
;     ...
;     const bf16* ap = GVT + ((tok0 >> 5) * 256 + g * 64 + r) * 32 + 8 * hh;
;     const float* wrow = wsp + (size_t)g * 128 * 128 + 8 * hh;
; #pragma unroll 4
;     for (int ks = 0; ks < nks; ++ks) {
;         const bf16* apk = ap + (ks >> 1) * (256 * 32) + 16 * (ks & 1);
;         const bf16x8 a0 = *(const bf16x8*)apk, a1 = *(const bf16x8*)(apk + 32 * 32);
;         const int pb = 16 * ks + 8 * hh;
;         float rs[8];
; #pragma unroll
;         for (int j = 0; j < 8; ++j) rs[j] = rstd[pb + j];
; #pragma unroll
;         for (int nt = 0; nt < 2; ++nt) {
;             const int t = 64 * th + 32 * nt + r; const float* wq = wrow + (size_t)t * 128 + 16 * ks;
;             const f32x4 w0 = *(const f32x4*)wq, w1 = *(const f32x4*)(wq + 4); float bv[8];
; #pragma unroll
;             for (int j = 0; j < 4; ++j) { bv[j] = (pb + j <= t) ? w0[j] * rs[j] : 0.f; bv[4 + j] = (pb + 4 + j <= t) ? w1[j] * rs[4 + j] : 0.f; }
;             const bf16x8 bf = pack8(bv);
;             acc[0][nt] = MFMA32(a0, bf, acc[0][nt]); acc[1][nt] = MFMA32(a1, bf, acc[1][nt]);
;         }
;     }
.LBB0_105:
	s_add_i32 s94, s9, 0xffffd000
	v_lshl_add_u64 v[84:85], s[94:95], 1, v[112:113]
	s_sub_i32 s94, s12, 48
	v_lshl_add_u64 v[74:75], s[94:95], 2, v[92:93]
	v_lshl_add_u64 v[72:73], v[74:75], 0, v[178:179]
	v_mov_b32_e32 v158, v110
	v_mov_b32_e32 v159, 0
	v_lshl_add_u64 v[148:149], v[74:75], 0, v[158:159]
	global_load_dwordx4 v[192:195], v[84:85], off
	global_load_dwordx4 v[196:199], v[84:85], off offset:2048
	global_load_dwordx4 v[200:203], v[72:73], off offset:16
	global_load_dwordx4 v[204:207], v[72:73], off
	global_load_dwordx4 v[208:211], v[148:149], off offset:16
	global_load_dwordx4 v[212:215], v[148:149], off
	global_load_dwordx4 v[216:219], v[84:85], off offset:32
	global_load_dwordx4 v[220:223], v[84:85], off offset:2080
	global_load_dwordx4 v[232:235], v[72:73], off offset:80
	global_load_dwordx4 v[236:239], v[72:73], off offset:64
	global_load_dwordx4 v[240:243], v[148:149], off offset:80
	global_load_dwordx4 v[244:247], v[148:149], off offset:64
	s_waitcnt vmcnt(0)
	s_nop 4
	v_mov_b32_e32 v64, v192
	v_mov_b32_e32 v65, v193
	v_mov_b32_e32 v66, v194
	v_mov_b32_e32 v67, v195
	s_nop 4
	v_mov_b32_e32 v68, v196
	v_mov_b32_e32 v69, v197
	v_mov_b32_e32 v70, v198
	v_mov_b32_e32 v71, v199
	ds_read_b128 v[76:79], v119
	ds_read_b128 v[80:83], v119 offset:16
	s_nop 4
	v_mov_b32_e32 v122, v200
	v_mov_b32_e32 v123, v201
	v_mov_b32_e32 v124, v202
	v_mov_b32_e32 v125, v203
	s_nop 4
	v_mov_b32_e32 v126, v204
	v_mov_b32_e32 v127, v205
	v_mov_b32_e32 v128, v206
	v_mov_b32_e32 v129, v207
	v_add_u32_e32 v120, s12, v116
	v_subrev_u32_e32 v114, 48, v120
	v_cmp_le_u32_e64 s[6:7], v114, v94
	s_add_i32 s94, s9, 0xfffff000
	s_mov_b32 s13, s95
	s_add_i32 s15, s15, -4
	s_waitcnt lgkmcnt(1)
	v_mul_f32_e32 v111, v76, v126
	v_cndmask_b32_e64 v111, 0, v111, s[6:7]
	v_cmp_lt_u32_e64 s[6:7], v114, v94
	v_mul_f32_e32 v115, v77, v127
	v_or_b32_e32 v127, 4, v114
	v_cndmask_b32_e64 v115, 0, v115, s[6:7]
	v_cvt_pk_bf16_f32 v130, v111, v115
	v_mov_b32_e32 v111, v179
	v_lshl_add_u64 v[74:75], v[74:75], 0, v[110:111]
	s_nop 4
	v_mov_b32_e32 v134, v208
	v_mov_b32_e32 v135, v209
	v_mov_b32_e32 v136, v210
	v_mov_b32_e32 v137, v211
	s_nop 4
	v_mov_b32_e32 v138, v212
	v_mov_b32_e32 v139, v213
	v_mov_b32_e32 v140, v214
	v_mov_b32_e32 v141, v215
	v_cmp_le_u32_e64 s[6:7], v114, v96
	v_or_b32_e32 v126, 5, v114
	v_mul_f32_e32 v76, v76, v138
	v_cndmask_b32_e64 v115, 0, v76, s[6:7]
	v_cmp_lt_u32_e64 s[6:7], v114, v96
	v_mul_f32_e32 v76, v77, v139
	s_nop 0
	v_cndmask_b32_e64 v121, 0, v76, s[6:7]
	s_waitcnt lgkmcnt(0)
	v_pk_mul_f32 v[76:77], v[80:81], v[122:123]
	v_cmp_le_u32_e64 s[6:7], v127, v94
	v_cvt_pk_bf16_f32 v76, v76, v77
	v_or_b32_e32 v123, 2, v114
	v_cndmask_b32_e64 v77, 0, v76, s[6:7]
	v_cmp_le_u32_e64 s[6:7], v126, v89
	v_lshrrev_b32_e32 v76, 16, v76
	v_or_b32_e32 v122, 3, v114
	v_cndmask_b32_e64 v76, 0, v76, s[6:7]
	v_perm_b32 v132, v76, v77, s52
	v_pk_mul_f32 v[76:77], v[78:79], v[128:129]
	v_cmp_le_u32_e64 s[6:7], v123, v94
	v_cvt_pk_bf16_f32 v76, v76, v77
	v_or_b32_e32 v128, 7, v114
	v_cndmask_b32_e64 v77, 0, v76, s[6:7]
	v_lshrrev_b32_e32 v76, 16, v76
	v_cmp_le_u32_e64 s[6:7], v122, v89
	v_or_b32_e32 v114, 6, v114
	v_pk_mul_f32 v[78:79], v[78:79], v[140:141]
	v_cndmask_b32_e64 v76, 0, v76, s[6:7]
	v_perm_b32 v131, v76, v77, s52
	v_pk_mul_f32 v[76:77], v[82:83], v[124:125]
	v_cmp_le_u32_e64 s[6:7], v114, v94
	v_cvt_pk_bf16_f32 v76, v76, v77
	v_pk_mul_f32 v[80:81], v[80:81], v[134:135]
	v_cndmask_b32_e64 v77, 0, v76, s[6:7]
	v_lshrrev_b32_e32 v76, 16, v76
	v_cmp_le_u32_e64 s[6:7], v128, v89
	v_pk_mul_f32 v[82:83], v[82:83], v[136:137]
	s_nop 0
	v_cndmask_b32_e64 v76, 0, v76, s[6:7]
	v_perm_b32 v133, v76, v77, s52
	v_cvt_pk_bf16_f32 v77, v78, v79
	v_cmp_le_u32_e64 s[6:7], v123, v96
	v_cvt_pk_bf16_f32 v76, v115, v121
	v_mfma_f32_32x32x16_bf16 v[48:63], v[64:67], v[130:133], v[48:63]
	v_cndmask_b32_e64 v78, 0, v77, s[6:7]
	v_lshrrev_b32_e32 v77, 16, v77
	v_cmp_le_u32_e64 s[6:7], v122, v87
	s_nop 1
	v_cndmask_b32_e64 v77, 0, v77, s[6:7]
	v_perm_b32 v77, v77, v78, s52
	v_cvt_pk_bf16_f32 v78, v80, v81
	v_cmp_le_u32_e64 s[6:7], v127, v96
	v_mfma_f32_32x32x16_bf16 v[16:31], v[68:71], v[130:133], v[16:31]
	s_nop 0
	v_cndmask_b32_e64 v79, 0, v78, s[6:7]
	v_cmp_le_u32_e64 s[6:7], v126, v87
	v_lshrrev_b32_e32 v78, 16, v78
	s_nop 0
	v_cndmask_b32_e64 v78, 0, v78, s[6:7]
	v_perm_b32 v78, v78, v79, s52
	v_cvt_pk_bf16_f32 v79, v82, v83
	v_cmp_le_u32_e64 s[6:7], v114, v96
	s_nop 1
	v_cndmask_b32_e64 v80, 0, v79, s[6:7]
	v_lshrrev_b32_e32 v79, 16, v79
	v_cmp_le_u32_e64 s[6:7], v128, v87
	s_nop 1
	v_cndmask_b32_e64 v79, 0, v79, s[6:7]
	v_perm_b32 v79, v79, v80, s52
	s_nop 1
	v_mfma_f32_32x32x16_bf16 v[32:47], v[64:67], v[76:79], v[32:47]
	v_mfma_f32_32x32x16_bf16 v[0:15], v[68:71], v[76:79], v[0:15]
	s_nop 4
	v_mov_b32_e32 v64, v216
	v_mov_b32_e32 v65, v217
	v_mov_b32_e32 v66, v218
	v_mov_b32_e32 v67, v219
	s_nop 4
	v_mov_b32_e32 v68, v220
	v_mov_b32_e32 v69, v221
	v_mov_b32_e32 v70, v222
	v_mov_b32_e32 v71, v223
	ds_read_b128 v[76:79], v119 offset:64
	s_nop 4
	v_mov_b32_e32 v80, v232
	v_mov_b32_e32 v81, v233
	v_mov_b32_e32 v82, v234
	v_mov_b32_e32 v83, v235
	s_nop 4
	v_mov_b32_e32 v122, v236
	v_mov_b32_e32 v123, v237
	v_mov_b32_e32 v124, v238
	v_mov_b32_e32 v125, v239
	s_nop 4
	v_mov_b32_e32 v126, v240
	v_mov_b32_e32 v127, v241
	v_mov_b32_e32 v128, v242
	v_mov_b32_e32 v129, v243
	s_nop 4
	v_mov_b32_e32 v130, v244
	v_mov_b32_e32 v131, v245
	v_mov_b32_e32 v132, v246
	v_mov_b32_e32 v133, v247
	v_subrev_u32_e32 v84, 32, v120
	ds_read_b128 v[134:137], v119 offset:80
	v_cmp_le_u32_e64 s[6:7], v84, v94
	v_or_b32_e32 v121, 4, v84
	v_or_b32_e32 v115, 5, v84
	s_waitcnt lgkmcnt(0)
; #define MFMA32(a, b, c) __builtin_amdgcn_mfma_f32_32x32x16_bf16((a), (b), (c), 0, 0, 0)
; __device__ __forceinline__ void gmlp_unit(const bf16* GVT, const bf16* U, const float* wsp, const float* bsp, const float* gain, bf16* OGM, int unit, LAS unsigned char* lds, int tid, int wave, int lane) {
;     ...
;     for (int ks = 0; ks < nks; ++ks) {
;         const bf16* apk = ap + (ks >> 1) * (256 * 32) + 16 * (ks & 1);
;         const bf16x8 a0 = *(const bf16x8*)apk, a1 = *(const bf16x8*)(apk + 32 * 32);
;         const int pb = 16 * ks + 8 * hh;
;         float rs[8];
; #pragma unroll
;         for (int j = 0; j < 8; ++j) rs[j] = rstd[pb + j];
; #pragma unroll
;         for (int nt = 0; nt < 2; ++nt) {
;             const int t = 64 * th + 32 * nt + r; const float* wq = wrow + (size_t)t * 128 + 16 * ks;
;             const f32x4 w0 = *(const f32x4*)wq, w1 = *(const f32x4*)(wq + 4); float bv[8];
; #pragma unroll
;             for (int j = 0; j < 4; ++j) { bv[j] = (pb + j <= t) ? w0[j] * rs[j] : 0.f; bv[4 + j] = (pb + 4 + j <= t) ? w1[j] * rs[4 + j] : 0.f; }
;             const bf16x8 bf = pack8(bv);
;             acc[0][nt] = MFMA32(a0, bf, acc[0][nt]); acc[1][nt] = MFMA32(a1, bf, acc[1][nt]);
;         }
;     }
	v_pk_mul_f32 v[74:75], v[134:135], v[80:81]
	v_mul_f32_e32 v72, v76, v122
	v_cndmask_b32_e64 v72, 0, v72, s[6:7]
	v_cmp_lt_u32_e64 s[6:7], v84, v94
	v_mul_f32_e32 v73, v77, v123
	v_or_b32_e32 v123, 2, v84
	v_cndmask_b32_e64 v73, 0, v73, s[6:7]
	v_cvt_pk_bf16_f32 v72, v72, v73
	v_mul_f32_e32 v73, v76, v130
	v_cmp_le_u32_e64 s[6:7], v84, v96
	v_pk_mul_f32 v[80:81], v[78:79], v[124:125]
	v_or_b32_e32 v122, 3, v84
	v_cndmask_b32_e64 v85, 0, v73, s[6:7]
	v_cmp_lt_u32_e64 s[6:7], v84, v96
	v_mul_f32_e32 v73, v77, v131
	v_or_b32_e32 v124, 7, v84
	v_cndmask_b32_e64 v114, 0, v73, s[6:7]
	v_cvt_pk_bf16_f32 v73, v74, v75
	v_cmp_le_u32_e64 s[6:7], v121, v94
	v_or_b32_e32 v84, 6, v84
	v_pk_mul_f32 v[78:79], v[78:79], v[132:133]
	v_cndmask_b32_e64 v74, 0, v73, s[6:7]
	v_cmp_le_u32_e64 s[6:7], v115, v89
	v_lshrrev_b32_e32 v73, 16, v73
	v_pk_mul_f32 v[76:77], v[134:135], v[126:127]
	v_cndmask_b32_e64 v73, 0, v73, s[6:7]
	v_perm_b32 v74, v73, v74, s52
	v_cvt_pk_bf16_f32 v73, v80, v81
	v_cmp_le_u32_e64 s[6:7], v123, v94
	v_pk_mul_f32 v[80:81], v[136:137], v[82:83]
	s_nop 0
	v_cndmask_b32_e64 v75, 0, v73, s[6:7]
	v_lshrrev_b32_e32 v73, 16, v73
	v_cmp_le_u32_e64 s[6:7], v122, v89
	s_nop 1
	v_cndmask_b32_e64 v73, 0, v73, s[6:7]
	v_perm_b32 v73, v73, v75, s52
	v_cvt_pk_bf16_f32 v75, v80, v81
	v_cmp_le_u32_e64 s[6:7], v84, v94
	s_nop 1
	v_cndmask_b32_e64 v80, 0, v75, s[6:7]
	v_lshrrev_b32_e32 v75, 16, v75
	v_cmp_le_u32_e64 s[6:7], v124, v89
	s_nop 1
	v_cndmask_b32_e64 v75, 0, v75, s[6:7]
	v_perm_b32 v75, v75, v80, s52
	v_cmp_le_u32_e64 s[6:7], v123, v96
	v_pk_mul_f32 v[80:81], v[136:137], v[128:129]
	v_mfma_f32_32x32x16_bf16 v[48:63], v[64:67], v[72:75], v[48:63]
	v_mfma_f32_32x32x16_bf16 v[16:31], v[68:71], v[72:75], v[16:31]
	v_cvt_pk_bf16_f32 v73, v78, v79
	v_cndmask_b32_e64 v74, 0, v73, s[6:7]
	v_lshrrev_b32_e32 v73, 16, v73
	v_cmp_le_u32_e64 s[6:7], v122, v87
	v_cvt_pk_bf16_f32 v72, v85, v114
	v_add_u32_e32 v114, -16, v120
	v_cndmask_b32_e64 v73, 0, v73, s[6:7]
	v_perm_b32 v73, v73, v74, s52
	v_cvt_pk_bf16_f32 v74, v76, v77
	v_cmp_le_u32_e64 s[6:7], v121, v96
	v_or_b32_e32 v121, 2, v114
	s_nop 0
	v_cndmask_b32_e64 v75, 0, v74, s[6:7]
	v_cmp_le_u32_e64 s[6:7], v115, v87
	v_lshrrev_b32_e32 v74, 16, v74
	v_or_b32_e32 v115, 3, v114
	v_cndmask_b32_e64 v74, 0, v74, s[6:7]
	v_perm_b32 v74, v74, v75, s52
	v_cvt_pk_bf16_f32 v75, v80, v81
	v_cmp_le_u32_e64 s[6:7], v84, v96
	s_nop 1
	v_cndmask_b32_e64 v76, 0, v75, s[6:7]
	v_lshrrev_b32_e32 v75, 16, v75
	v_cmp_le_u32_e64 s[6:7], v124, v87
	s_nop 1
	v_cndmask_b32_e64 v75, 0, v75, s[6:7]
	v_perm_b32 v75, v75, v76, s52
	v_cmp_le_u32_e64 s[6:7], v114, v94
	s_nop 0
	v_mfma_f32_32x32x16_bf16 v[0:15], v[68:71], v[72:75], v[0:15]
	v_lshl_add_u64 v[68:69], s[94:95], 1, v[112:113]
	s_add_i32 s94, s12, -16
	v_lshl_add_u64 v[84:85], s[94:95], 2, v[92:93]
	v_lshl_add_u64 v[80:81], v[84:85], 0, v[178:179]
	v_mov_b32_e32 v158, v110
	v_mov_b32_e32 v159, 0
	v_lshl_add_u64 v[148:149], v[84:85], 0, v[158:159]
	s_and_b32 s94, s9, 0x7fffe000
	s_lshl_b32 s94, s94, 1
	v_lshl_add_u64 v[150:151], v[112:113], 0, s[94:95]
	v_lshl_add_u64 v[152:153], s[12:13], 2, v[92:93]
	v_lshl_add_u64 v[154:155], v[152:153], 0, v[178:179]
	v_lshl_add_u64 v[156:157], v[152:153], 0, v[158:159]
	global_load_dwordx4 v[192:195], v[68:69], off
	global_load_dwordx4 v[196:199], v[68:69], off offset:2048
	global_load_dwordx4 v[200:203], v[80:81], off offset:16
	global_load_dwordx4 v[204:207], v[80:81], off
	global_load_dwordx4 v[208:211], v[148:149], off offset:16
	global_load_dwordx4 v[212:215], v[148:149], off
	global_load_dwordx4 v[216:219], v[150:151], off offset:32
	global_load_dwordx4 v[220:223], v[150:151], off offset:2080
	global_load_dwordx4 v[232:235], v[154:155], off offset:16
	global_load_dwordx4 v[236:239], v[154:155], off
	global_load_dwordx4 v[240:243], v[156:157], off offset:16
	global_load_dwordx4 v[244:247], v[156:157], off
	s_waitcnt vmcnt(0)
	v_mfma_f32_32x32x16_bf16 v[32:47], v[64:67], v[72:75], v[32:47]
	s_nop 4
	v_mov_b32_e32 v64, v192
	v_mov_b32_e32 v65, v193
	v_mov_b32_e32 v66, v194
	v_mov_b32_e32 v67, v195
	s_nop 0
	s_nop 4
	v_mov_b32_e32 v68, v196
	v_mov_b32_e32 v69, v197
	v_mov_b32_e32 v70, v198
	v_mov_b32_e32 v71, v199
	ds_read_b128 v[72:75], v119 offset:128
	s_nop 4
	v_mov_b32_e32 v76, v200
	v_mov_b32_e32 v77, v201
	v_mov_b32_e32 v78, v202
	v_mov_b32_e32 v79, v203
	s_nop 0
	s_nop 4
	v_mov_b32_e32 v80, v204
	v_mov_b32_e32 v81, v205
	v_mov_b32_e32 v82, v206
	v_mov_b32_e32 v83, v207
	s_waitcnt lgkmcnt(0)
	v_mul_f32_e32 v80, v72, v80
	v_cndmask_b32_e64 v80, 0, v80, s[6:7]
	v_cmp_lt_u32_e64 s[6:7], v114, v94
	v_mul_f32_e32 v81, v73, v81
	s_nop 0
	v_cndmask_b32_e64 v81, 0, v81, s[6:7]
	v_cvt_pk_bf16_f32 v122, v80, v81
	v_lshl_add_u64 v[80:81], v[84:85], 0, v[110:111]
	s_nop 4
	v_mov_b32_e32 v126, v208
	v_mov_b32_e32 v127, v209
	v_mov_b32_e32 v128, v210
	v_mov_b32_e32 v129, v211
	s_nop 4
	v_mov_b32_e32 v130, v212
	v_mov_b32_e32 v131, v213
	v_mov_b32_e32 v132, v214
	v_mov_b32_e32 v133, v215
	ds_read_b128 v[134:137], v119 offset:144
	v_cmp_le_u32_e64 s[6:7], v114, v96
	v_or_b32_e32 v85, 4, v114
	v_or_b32_e32 v84, 5, v114
	v_mul_f32_e32 v72, v72, v130
	v_cndmask_b32_e64 v80, 0, v72, s[6:7]
	v_cmp_lt_u32_e64 s[6:7], v114, v96
	v_mul_f32_e32 v72, v73, v131
	s_nop 0
	v_cndmask_b32_e64 v81, 0, v72, s[6:7]
	s_waitcnt lgkmcnt(0)
; #define MFMA32(a, b, c) __builtin_amdgcn_mfma_f32_32x32x16_bf16((a), (b), (c), 0, 0, 0)
; __device__ __forceinline__ void gmlp_unit(const bf16* GVT, const bf16* U, const float* wsp, const float* bsp, const float* gain, bf16* OGM, int unit, LAS unsigned char* lds, int tid, int wave, int lane) {
;     ...
;     for (int ks = 0; ks < nks; ++ks) {
;         const bf16* apk = ap + (ks >> 1) * (256 * 32) + 16 * (ks & 1);
;         const bf16x8 a0 = *(const bf16x8*)apk, a1 = *(const bf16x8*)(apk + 32 * 32);
;         const int pb = 16 * ks + 8 * hh;
;         float rs[8];
; #pragma unroll
;         for (int j = 0; j < 8; ++j) rs[j] = rstd[pb + j];
; #pragma unroll
;         for (int nt = 0; nt < 2; ++nt) {
;             const int t = 64 * th + 32 * nt + r; const float* wq = wrow + (size_t)t * 128 + 16 * ks;
;             const f32x4 w0 = *(const f32x4*)wq, w1 = *(const f32x4*)(wq + 4); float bv[8];
; #pragma unroll
;             for (int j = 0; j < 4; ++j) { bv[j] = (pb + j <= t) ? w0[j] * rs[j] : 0.f; bv[4 + j] = (pb + 4 + j <= t) ? w1[j] * rs[4 + j] : 0.f; }
;             const bf16x8 bf = pack8(bv);
;             acc[0][nt] = MFMA32(a0, bf, acc[0][nt]); acc[1][nt] = MFMA32(a1, bf, acc[1][nt]);
;         }
;     }
	v_pk_mul_f32 v[72:73], v[134:135], v[76:77]
	v_cmp_le_u32_e64 s[6:7], v85, v94
	v_cvt_pk_bf16_f32 v72, v72, v73
	v_pk_mul_f32 v[76:77], v[134:135], v[126:127]
	v_cndmask_b32_e64 v73, 0, v72, s[6:7]
	v_cmp_le_u32_e64 s[6:7], v84, v89
	v_lshrrev_b32_e32 v72, 16, v72
	s_nop 0
	v_cndmask_b32_e64 v72, 0, v72, s[6:7]
	v_perm_b32 v124, v72, v73, s52
	v_pk_mul_f32 v[72:73], v[74:75], v[82:83]
	v_cmp_le_u32_e64 s[6:7], v121, v94
	v_cvt_pk_bf16_f32 v72, v72, v73
	v_or_b32_e32 v83, 6, v114
	v_cndmask_b32_e64 v73, 0, v72, s[6:7]
	v_lshrrev_b32_e32 v72, 16, v72
	v_cmp_le_u32_e64 s[6:7], v115, v89
	v_or_b32_e32 v82, 7, v114
	v_pk_mul_f32 v[74:75], v[74:75], v[132:133]
	v_cndmask_b32_e64 v72, 0, v72, s[6:7]
	v_perm_b32 v123, v72, v73, s52
	v_pk_mul_f32 v[72:73], v[136:137], v[78:79]
	v_cmp_le_u32_e64 s[6:7], v83, v94
	v_cvt_pk_bf16_f32 v72, v72, v73
	v_pk_mul_f32 v[78:79], v[136:137], v[128:129]
	v_cndmask_b32_e64 v73, 0, v72, s[6:7]
	v_lshrrev_b32_e32 v72, 16, v72
	v_cmp_le_u32_e64 s[6:7], v82, v89
	s_nop 1
	v_cndmask_b32_e64 v72, 0, v72, s[6:7]
	v_perm_b32 v125, v72, v73, s52
	v_cvt_pk_bf16_f32 v73, v74, v75
	v_cmp_le_u32_e64 s[6:7], v121, v96
	v_cvt_pk_bf16_f32 v72, v80, v81
	v_mfma_f32_32x32x16_bf16 v[48:63], v[64:67], v[122:125], v[48:63]
	v_cndmask_b32_e64 v74, 0, v73, s[6:7]
	v_lshrrev_b32_e32 v73, 16, v73
	v_cmp_le_u32_e64 s[6:7], v115, v87
	v_or_b32_e32 v121, 5, v120
	s_nop 0
	v_cndmask_b32_e64 v73, 0, v73, s[6:7]
	v_perm_b32 v73, v73, v74, s52
	v_cvt_pk_bf16_f32 v74, v76, v77
	v_cmp_le_u32_e64 s[6:7], v85, v96
	v_mfma_f32_32x32x16_bf16 v[16:31], v[68:71], v[122:125], v[16:31]
	s_nop 0
	v_cndmask_b32_e64 v75, 0, v74, s[6:7]
	v_cmp_le_u32_e64 s[6:7], v84, v87
	v_lshrrev_b32_e32 v74, 16, v74
	s_nop 0
	v_cndmask_b32_e64 v74, 0, v74, s[6:7]
	v_perm_b32 v74, v74, v75, s52
	v_cvt_pk_bf16_f32 v75, v78, v79
	v_cmp_le_u32_e64 s[6:7], v83, v96
	s_nop 1
	v_cndmask_b32_e64 v76, 0, v75, s[6:7]
	v_lshrrev_b32_e32 v75, 16, v75
	v_cmp_le_u32_e64 s[6:7], v82, v87
	s_nop 1
	v_cndmask_b32_e64 v75, 0, v75, s[6:7]
	v_perm_b32 v75, v75, v76, s52
	s_and_b32 s6, s9, 0x7fffe000
	s_lshl_b32 s94, s6, 1
	v_mfma_f32_32x32x16_bf16 v[32:47], v[64:67], v[72:75], v[32:47]
	v_lshl_add_u64 v[64:65], v[112:113], 0, s[94:95]
	v_cmp_le_u32_e64 s[6:7], v120, v94
	s_addk_i32 s9, 0x4000
	v_mfma_f32_32x32x16_bf16 v[0:15], v[68:71], v[72:75], v[0:15]
	v_lshl_add_u64 v[72:73], s[12:13], 2, v[92:93]
	v_lshl_add_u64 v[74:75], v[72:73], 0, v[178:179]
	s_nop 4
	v_mov_b32_e32 v68, v216
	v_mov_b32_e32 v69, v217
	v_mov_b32_e32 v70, v218
	v_mov_b32_e32 v71, v219
	s_nop 0
	s_nop 4
	v_mov_b32_e32 v64, v220
	v_mov_b32_e32 v65, v221
	v_mov_b32_e32 v66, v222
	v_mov_b32_e32 v67, v223
	ds_read_b128 v[122:125], v119 offset:192
	s_nop 4
	v_mov_b32_e32 v78, v232
	v_mov_b32_e32 v79, v233
	v_mov_b32_e32 v80, v234
	v_mov_b32_e32 v81, v235
	s_nop 4
	v_mov_b32_e32 v126, v236
	v_mov_b32_e32 v127, v237
	v_mov_b32_e32 v128, v238
	v_mov_b32_e32 v129, v239
	v_lshl_add_u64 v[82:83], v[72:73], 0, v[110:111]
	v_or_b32_e32 v111, 7, v120
	s_add_i32 s12, s12, 64
	s_cmp_lg_u32 s15, 0
	s_waitcnt lgkmcnt(0)
	v_mul_f32_e32 v74, v122, v126
	v_cndmask_b32_e64 v74, 0, v74, s[6:7]
	v_cmp_lt_u32_e64 s[6:7], v120, v94
	v_mul_f32_e32 v75, v123, v127
	v_or_b32_e32 v127, 3, v120
	v_cndmask_b32_e64 v75, 0, v75, s[6:7]
	v_cvt_pk_bf16_f32 v76, v74, v75
	s_nop 4
	v_mov_b32_e32 v72, v240
	v_mov_b32_e32 v73, v241
	v_mov_b32_e32 v74, v242
	v_mov_b32_e32 v75, v243
	s_nop 4
	v_mov_b32_e32 v130, v244
	v_mov_b32_e32 v131, v245
	v_mov_b32_e32 v132, v246
	v_mov_b32_e32 v133, v247
	ds_read_b128 v[82:85], v119 offset:208
	v_cmp_le_u32_e64 s[6:7], v120, v96
	v_add_u32_e32 v119, 0x100, v119
	s_waitcnt lgkmcnt(0)
	v_pk_mul_f32 v[78:79], v[82:83], v[78:79]
	v_pk_mul_f32 v[82:83], v[82:83], v[72:73]
	v_mul_f32_e32 v77, v122, v130
	v_cndmask_b32_e64 v126, 0, v77, s[6:7]
	v_cmp_lt_u32_e64 s[6:7], v120, v96
	v_mul_f32_e32 v77, v123, v131
	v_or_b32_e32 v122, 4, v120
	v_cndmask_b32_e64 v123, 0, v77, s[6:7]
	v_cvt_pk_bf16_f32 v77, v78, v79
	v_cmp_le_u32_e64 s[6:7], v122, v94
	v_or_b32_e32 v130, 2, v120
	v_pk_mul_f32 v[72:73], v[124:125], v[128:129]
	v_cndmask_b32_e64 v78, 0, v77, s[6:7]
	v_cmp_le_u32_e64 s[6:7], v121, v89
	v_lshrrev_b32_e32 v77, 16, v77
	v_cvt_pk_bf16_f32 v72, v72, v73
	v_cndmask_b32_e64 v77, 0, v77, s[6:7]
	v_cmp_le_u32_e64 s[6:7], v130, v94
	v_perm_b32 v78, v77, v78, s52
	v_or_b32_e32 v120, 6, v120
	v_cndmask_b32_e64 v73, 0, v72, s[6:7]
	v_lshrrev_b32_e32 v72, 16, v72
	v_cmp_le_u32_e64 s[6:7], v127, v89
	v_pk_mul_f32 v[114:115], v[124:125], v[132:133]
	s_nop 0
	v_cndmask_b32_e64 v72, 0, v72, s[6:7]
	v_perm_b32 v77, v72, v73, s52
	v_pk_mul_f32 v[72:73], v[84:85], v[80:81]
	v_cmp_le_u32_e64 s[6:7], v120, v94
	v_cvt_pk_bf16_f32 v72, v72, v73
	s_nop 0
	v_cndmask_b32_e64 v73, 0, v72, s[6:7]
	v_lshrrev_b32_e32 v72, 16, v72
	v_cmp_le_u32_e64 s[6:7], v111, v89
	s_nop 1
	v_cndmask_b32_e64 v72, 0, v72, s[6:7]
	v_perm_b32 v79, v72, v73, s52
	v_cvt_pk_bf16_f32 v73, v114, v115
	v_cmp_le_u32_e64 s[6:7], v130, v96
	v_mfma_f32_32x32x16_bf16 v[48:63], v[68:71], v[76:79], v[48:63]
	v_cvt_pk_bf16_f32 v72, v126, v123
	v_mfma_f32_32x32x16_bf16 v[16:31], v[64:67], v[76:79], v[16:31]
	v_mul_f32_e64 v76, v84, v74
	v_mul_f32_e64 v77, v85, v75
	v_cndmask_b32_e64 v74, 0, v73, s[6:7]
	v_lshrrev_b32_e32 v73, 16, v73
	v_cmp_le_u32_e64 s[6:7], v127, v87
	s_nop 1
	v_cndmask_b32_e64 v73, 0, v73, s[6:7]
	v_perm_b32 v73, v73, v74, s52
	v_cvt_pk_bf16_f32 v74, v82, v83
	v_cmp_le_u32_e64 s[6:7], v122, v96
	s_nop 1
	v_cndmask_b32_e64 v75, 0, v74, s[6:7]
	v_cmp_le_u32_e64 s[6:7], v121, v87
	v_lshrrev_b32_e32 v74, 16, v74
	s_nop 0
	v_cndmask_b32_e64 v74, 0, v74, s[6:7]
	v_perm_b32 v74, v74, v75, s52
	v_cvt_pk_bf16_f32 v75, v76, v77
	v_cmp_le_u32_e64 s[6:7], v120, v96
	s_nop 1
	v_cndmask_b32_e64 v76, 0, v75, s[6:7]
	v_lshrrev_b32_e32 v75, 16, v75
	v_cmp_le_u32_e64 s[6:7], v111, v87
	s_nop 1
	v_cndmask_b32_e64 v75, 0, v75, s[6:7]
	v_perm_b32 v75, v75, v76, s52
	s_nop 1
	v_mfma_f32_32x32x16_bf16 v[32:47], v[68:71], v[72:75], v[32:47]
	v_mfma_f32_32x32x16_bf16 v[0:15], v[64:67], v[72:75], v[0:15]
	s_cbranch_scc1 .LBB0_105
; __device__ __forceinline__ unsigned pk2(float lo, float hi) { f32v2 v = {lo, hi}; bf16v2 r = __builtin_convertvector(v, bf16v2); return __builtin_bit_cast(unsigned, r); }
; __device__ __forceinline__ void gmlp_unit(const bf16* GVT, const bf16* U, const float* wsp, const float* bsp, const float* gain, bf16* OGM, int unit, LAS unsigned char* lds, int tid, int wave, int lane) {
;     ...
; #pragma unroll
;     for (int mt = 0; mt < 2; ++mt)
; #pragma unroll
;         for (int nt = 0; nt < 2; ++nt) {
;             const int t = 64 * th + 32 * nt + r; const float bias = bsp[g * 128 + t];
; #pragma unroll
;             for (int gp = 0; gp < 2; ++gp) {
;                 v2u pc[2];
; #pragma unroll
;                 for (int e = 0; e < 2; ++e) { const int q4 = 2 * gp + e;
;                     const int c = g * 64 + mt * 32 + 8 * q4 + 4 * hh;
;                     const f32x4 gn = *(const f32x4*)(gain + c);
;                     const v2u uw = *(const v2u*)(U + (tok0 + t) * 256 + c);
;                     const float v0 = (acc[mt][nt][4 * q4] * gn.x + bias) * bf_lo(uw.x), v1 = (acc[mt][nt][4 * q4 + 1] * gn.y + bias) * bf_hi(uw.x);
;                     const float v2 = (acc[mt][nt][4 * q4 + 2] * gn.z + bias) * bf_lo(uw.y), v3 = (acc[mt][nt][4 * q4 + 3] * gn.w + bias) * bf_hi(uw.y);
;                     pc[e].x = pk2(v0, v1); pc[e].y = pk2(v2, v3); }
;                 *(v4u*)(OGM + (tok0 + t) * 256 + g * 64 + mt * 32 + 8 * (2 * gp + hh)) = pair_widen(pc[0], pc[1], hh);
;             }
;         }
	v_mov_b32_e32 v65, s11
	v_or_b32_e32 v64, s10, v94
	v_lshlrev_b64 v[76:77], 9, v[64:65]
	v_lshl_add_u64 v[64:65], v[106:107], 0, v[76:77]
	v_mov_b32_e32 v249, s11
	v_or_b32_e32 v248, s10, v96
	v_lshlrev_b64 v[248:249], 9, v[248:249]
	v_lshl_add_u64 v[182:183], v[106:107], 0, v[248:249]
	global_load_dwordx4 v[192:195], v[98:99], off
	global_load_dwordx4 v[196:199], v[98:99], off offset:32
	global_load_dwordx4 v[200:203], v[98:99], off offset:64
	global_load_dwordx4 v[204:207], v[98:99], off offset:96
	global_load_dwordx4 v[208:211], v[98:99], off offset:128
	global_load_dwordx4 v[212:215], v[98:99], off offset:160
	global_load_dwordx4 v[216:219], v[98:99], off offset:192
	global_load_dwordx4 v[220:223], v[98:99], off offset:224
	global_load_dword v180, v[100:101], off
	global_load_dword v181, v[102:103], off offset:128
	global_load_dwordx2 v[148:149], v[64:65], off
	global_load_dwordx2 v[150:151], v[64:65], off offset:16
	global_load_dwordx2 v[152:153], v[64:65], off offset:32
	global_load_dwordx2 v[154:155], v[64:65], off offset:48
	global_load_dwordx2 v[156:157], v[64:65], off offset:64
	global_load_dwordx2 v[158:159], v[64:65], off offset:80
	global_load_dwordx2 v[160:161], v[64:65], off offset:96
	global_load_dwordx2 v[162:163], v[64:65], off offset:112
	global_load_dwordx2 v[232:233], v[182:183], off
	global_load_dwordx2 v[234:235], v[182:183], off offset:16
	global_load_dwordx2 v[236:237], v[182:183], off offset:32
	global_load_dwordx2 v[238:239], v[182:183], off offset:48
	global_load_dwordx2 v[240:241], v[182:183], off offset:64
	global_load_dwordx2 v[242:243], v[182:183], off offset:80
	global_load_dwordx2 v[244:245], v[182:183], off offset:96
	global_load_dwordx2 v[246:247], v[182:183], off offset:112
	s_waitcnt vmcnt(0)
	s_nop 1
	v_mov_b32_e32 v74, v180
	s_nop 1
	v_mov_b32_e32 v66, v192
	v_mov_b32_e32 v67, v193
	v_mov_b32_e32 v68, v194
	v_mov_b32_e32 v69, v195
	s_nop 1
	v_mov_b32_e32 v70, v196
	v_mov_b32_e32 v71, v197
	v_mov_b32_e32 v72, v198
	v_mov_b32_e32 v73, v199
	s_nop 1
	v_mov_b32_e32 v78, v148
	v_mov_b32_e32 v79, v149
	s_nop 1
	v_mov_b32_e32 v80, v150
	v_mov_b32_e32 v81, v151
	s_add_i32 s8, s8, s82
	s_cmpk_gt_i32 s8, 0xff
	v_pk_fma_f32 v[50:51], v[50:51], v[68:69], v[74:75] op_sel_hi:[1,1,0]
	v_pk_fma_f32 v[54:55], v[54:55], v[72:73], v[74:75] op_sel_hi:[1,1,0]
	v_lshlrev_b32_e32 v68, 16, v79
	v_and_b32_e32 v69, 0xffff0000, v79
	v_lshlrev_b32_e32 v72, 16, v81
	v_and_b32_e32 v73, 0xffff0000, v81
	v_pk_fma_f32 v[48:49], v[48:49], v[66:67], v[74:75] op_sel_hi:[1,1,0]
	v_pk_fma_f32 v[52:53], v[52:53], v[70:71], v[74:75] op_sel_hi:[1,1,0]
	v_lshlrev_b32_e32 v66, 16, v78
	v_and_b32_e32 v67, 0xffff0000, v78
	v_lshlrev_b32_e32 v70, 16, v80
	v_and_b32_e32 v71, 0xffff0000, v80
	v_pk_mul_f32 v[50:51], v[50:51], v[68:69]
	v_pk_mul_f32 v[54:55], v[54:55], v[72:73]
	v_pk_mul_f32 v[48:49], v[48:49], v[66:67]
	v_pk_mul_f32 v[52:53], v[52:53], v[70:71]
	v_cvt_pk_bf16_f32 v50, v50, v51
	v_cvt_pk_bf16_f32 v51, v54, v55
	v_cvt_pk_bf16_f32 v66, v48, v49
	v_cvt_pk_bf16_f32 v52, v52, v53
	v_cndmask_b32_e64 v48, v50, v51, s[4:5]
	ds_bpermute_b32 v54, v117, v48
	v_cndmask_b32_e64 v48, v66, v52, s[4:5]
	ds_bpermute_b32 v55, v117, v48
	v_lshl_add_u64 v[48:49], v[108:109], 0, v[76:77]
	v_mov_b32_e32 v73, s11
	s_waitcnt lgkmcnt(1)
	v_cndmask_b32_e64 v53, v51, v54, s[4:5]
	v_cndmask_b32_e64 v51, v54, v50, s[4:5]
	s_waitcnt lgkmcnt(0)
	v_cndmask_b32_e64 v52, v52, v55, s[4:5]
	v_cndmask_b32_e64 v50, v55, v66, s[4:5]
	global_store_dwordx4 v[48:49], v[50:53], off sc0 sc1
	s_nop 1
	v_mov_b32_e32 v50, v200
	v_mov_b32_e32 v51, v201
	v_mov_b32_e32 v52, v202
	v_mov_b32_e32 v53, v203
	s_nop 0
	s_nop 1
	v_mov_b32_e32 v54, v152
	v_mov_b32_e32 v55, v153
	s_nop 1
	v_mov_b32_e32 v66, v204
	v_mov_b32_e32 v67, v205
	v_mov_b32_e32 v68, v206
	v_mov_b32_e32 v69, v207
	s_nop 1
	v_mov_b32_e32 v70, v154
	v_mov_b32_e32 v71, v155
	v_or_b32_e32 v72, s10, v96
	v_pk_fma_f32 v[50:51], v[56:57], v[50:51], v[74:75] op_sel_hi:[1,1,0]
	v_lshlrev_b32_e32 v56, 16, v54
	v_and_b32_e32 v57, 0xffff0000, v54
	v_pk_fma_f32 v[52:53], v[58:59], v[52:53], v[74:75] op_sel_hi:[1,1,0]
	v_lshlrev_b32_e32 v54, 16, v55
	v_and_b32_e32 v55, 0xffff0000, v55
	v_pk_fma_f32 v[58:59], v[60:61], v[66:67], v[74:75] op_sel_hi:[1,1,0]
	v_pk_fma_f32 v[62:63], v[62:63], v[68:69], v[74:75] op_sel_hi:[1,1,0]
	v_lshlrev_b32_e32 v66, 16, v71
	v_and_b32_e32 v67, 0xffff0000, v71
	v_lshlrev_b32_e32 v60, 16, v70
	v_and_b32_e32 v61, 0xffff0000, v70
	v_pk_mul_f32 v[50:51], v[50:51], v[56:57]
	v_pk_mul_f32 v[52:53], v[52:53], v[54:55]
	v_pk_mul_f32 v[56:57], v[62:63], v[66:67]
	v_pk_mul_f32 v[54:55], v[58:59], v[60:61]
	v_cvt_pk_bf16_f32 v52, v52, v53
	v_cvt_pk_bf16_f32 v53, v56, v57
	v_cvt_pk_bf16_f32 v58, v50, v51
	v_cvt_pk_bf16_f32 v54, v54, v55
	v_cndmask_b32_e64 v50, v52, v53, s[4:5]
	ds_bpermute_b32 v56, v117, v50
	v_cndmask_b32_e64 v50, v58, v54, s[4:5]
	ds_bpermute_b32 v57, v117, v50
	v_lshlrev_b64 v[60:61], 9, v[72:73]
	v_lshl_add_u64 v[50:51], v[106:107], 0, v[60:61]
	s_waitcnt lgkmcnt(1)
	v_cndmask_b32_e64 v55, v53, v56, s[4:5]
	v_cndmask_b32_e64 v53, v56, v52, s[4:5]
	s_waitcnt lgkmcnt(0)
; __device__ __forceinline__ unsigned pk2(float lo, float hi) { f32v2 v = {lo, hi}; bf16v2 r = __builtin_convertvector(v, bf16v2); return __builtin_bit_cast(unsigned, r); }
; __device__ __forceinline__ void gmlp_unit(const bf16* GVT, const bf16* U, const float* wsp, const float* bsp, const float* gain, bf16* OGM, int unit, LAS unsigned char* lds, int tid, int wave, int lane) {
;     ...
;             for (int gp = 0; gp < 2; ++gp) {
;                 v2u pc[2];
; #pragma unroll
;                 for (int e = 0; e < 2; ++e) { const int q4 = 2 * gp + e;
;                     const int c = g * 64 + mt * 32 + 8 * q4 + 4 * hh;
;                     const f32x4 gn = *(const f32x4*)(gain + c);
;                     const v2u uw = *(const v2u*)(U + (tok0 + t) * 256 + c);
;                     const float v0 = (acc[mt][nt][4 * q4] * gn.x + bias) * bf_lo(uw.x), v1 = (acc[mt][nt][4 * q4 + 1] * gn.y + bias) * bf_hi(uw.x);
;                     const float v2 = (acc[mt][nt][4 * q4 + 2] * gn.z + bias) * bf_lo(uw.y), v3 = (acc[mt][nt][4 * q4 + 3] * gn.w + bias) * bf_hi(uw.y);
;                     pc[e].x = pk2(v0, v1); pc[e].y = pk2(v2, v3); }
;                 *(v4u*)(OGM + (tok0 + t) * 256 + g * 64 + mt * 32 + 8 * (2 * gp + hh)) = pair_widen(pc[0], pc[1], hh);
	v_cndmask_b32_e64 v54, v54, v57, s[4:5]
	v_cndmask_b32_e64 v52, v57, v58, s[4:5]
	global_store_dwordx4 v[48:49], v[52:55], off offset:32 sc0 sc1
	s_nop 1
	v_mov_b32_e32 v62, v181
	s_nop 0
	s_nop 1
	v_mov_b32_e32 v52, v192
	v_mov_b32_e32 v53, v193
	v_mov_b32_e32 v54, v194
	v_mov_b32_e32 v55, v195
	s_nop 1
	v_mov_b32_e32 v66, v232
	v_mov_b32_e32 v67, v233
	s_nop 1
	v_mov_b32_e32 v56, v196
	v_mov_b32_e32 v57, v197
	v_mov_b32_e32 v58, v198
	v_mov_b32_e32 v59, v199
	s_nop 1
	v_mov_b32_e32 v68, v234
	v_mov_b32_e32 v69, v235
	v_pk_fma_f32 v[34:35], v[34:35], v[54:55], v[62:63] op_sel_hi:[1,1,0]
	v_lshlrev_b32_e32 v54, 16, v67
	v_and_b32_e32 v55, 0xffff0000, v67
	v_pk_fma_f32 v[38:39], v[38:39], v[58:59], v[62:63] op_sel_hi:[1,1,0]
	v_lshlrev_b32_e32 v58, 16, v69
	v_and_b32_e32 v59, 0xffff0000, v69
	v_pk_fma_f32 v[32:33], v[32:33], v[52:53], v[62:63] op_sel_hi:[1,1,0]
	v_lshlrev_b32_e32 v52, 16, v66
	v_and_b32_e32 v53, 0xffff0000, v66
	v_pk_fma_f32 v[36:37], v[36:37], v[56:57], v[62:63] op_sel_hi:[1,1,0]
	v_lshlrev_b32_e32 v56, 16, v68
	v_and_b32_e32 v57, 0xffff0000, v68
	v_pk_mul_f32 v[34:35], v[34:35], v[54:55]
	v_pk_mul_f32 v[38:39], v[38:39], v[58:59]
	v_pk_mul_f32 v[32:33], v[32:33], v[52:53]
	v_pk_mul_f32 v[36:37], v[36:37], v[56:57]
	v_cvt_pk_bf16_f32 v34, v34, v35
	v_cvt_pk_bf16_f32 v35, v38, v39
	v_cvt_pk_bf16_f32 v52, v32, v33
	v_cvt_pk_bf16_f32 v36, v36, v37
	v_cndmask_b32_e64 v32, v34, v35, s[4:5]
	ds_bpermute_b32 v38, v117, v32
	v_cndmask_b32_e64 v32, v52, v36, s[4:5]
	ds_bpermute_b32 v39, v117, v32
	v_lshl_add_u64 v[32:33], v[108:109], 0, v[60:61]
	s_waitcnt lgkmcnt(1)
	v_cndmask_b32_e64 v37, v35, v38, s[4:5]
	v_cndmask_b32_e64 v35, v38, v34, s[4:5]
	s_waitcnt lgkmcnt(0)
	v_cndmask_b32_e64 v36, v36, v39, s[4:5]
	v_cndmask_b32_e64 v34, v39, v52, s[4:5]
	global_store_dwordx4 v[32:33], v[34:37], off sc0 sc1
	s_nop 1
	v_mov_b32_e32 v34, v200
	v_mov_b32_e32 v35, v201
	v_mov_b32_e32 v36, v202
	v_mov_b32_e32 v37, v203
	s_nop 0
	s_nop 1
	v_mov_b32_e32 v38, v236
	v_mov_b32_e32 v39, v237
	s_nop 1
	v_mov_b32_e32 v52, v204
	v_mov_b32_e32 v53, v205
	v_mov_b32_e32 v54, v206
	v_mov_b32_e32 v55, v207
	s_nop 1
	v_mov_b32_e32 v56, v238
	v_mov_b32_e32 v57, v239
	v_pk_fma_f32 v[34:35], v[40:41], v[34:35], v[62:63] op_sel_hi:[1,1,0]
	v_lshlrev_b32_e32 v40, 16, v38
	v_and_b32_e32 v41, 0xffff0000, v38
	v_pk_fma_f32 v[36:37], v[42:43], v[36:37], v[62:63] op_sel_hi:[1,1,0]
	v_lshlrev_b32_e32 v38, 16, v39
	v_and_b32_e32 v39, 0xffff0000, v39
	v_pk_fma_f32 v[42:43], v[44:45], v[52:53], v[62:63] op_sel_hi:[1,1,0]
	v_lshlrev_b32_e32 v44, 16, v56
	v_and_b32_e32 v45, 0xffff0000, v56
	v_pk_fma_f32 v[46:47], v[46:47], v[54:55], v[62:63] op_sel_hi:[1,1,0]
	v_lshlrev_b32_e32 v52, 16, v57
	v_and_b32_e32 v53, 0xffff0000, v57
	v_pk_mul_f32 v[34:35], v[34:35], v[40:41]
	v_pk_mul_f32 v[36:37], v[36:37], v[38:39]
	v_pk_mul_f32 v[38:39], v[42:43], v[44:45]
	v_pk_mul_f32 v[40:41], v[46:47], v[52:53]
	v_cvt_pk_bf16_f32 v34, v34, v35
	v_cvt_pk_bf16_f32 v35, v36, v37
	v_cvt_pk_bf16_f32 v36, v38, v39
	v_cvt_pk_bf16_f32 v37, v40, v41
	v_cndmask_b32_e64 v38, v35, v37, s[4:5]
	v_cndmask_b32_e64 v39, v34, v36, s[4:5]
	ds_bpermute_b32 v38, v117, v38
	ds_bpermute_b32 v39, v117, v39
	s_waitcnt lgkmcnt(1)
	v_cndmask_b32_e64 v37, v37, v38, s[4:5]
	v_cndmask_b32_e64 v35, v38, v35, s[4:5]
	s_waitcnt lgkmcnt(0)
	v_cndmask_b32_e64 v36, v36, v39, s[4:5]
	v_cndmask_b32_e64 v34, v39, v34, s[4:5]
	global_store_dwordx4 v[32:33], v[34:37], off offset:32 sc0 sc1
	s_nop 1
	v_mov_b32_e32 v42, v180
	s_nop 0
	s_nop 1
	v_mov_b32_e32 v34, v208
	v_mov_b32_e32 v35, v209
	v_mov_b32_e32 v36, v210
	v_mov_b32_e32 v37, v211
	s_nop 1
	v_mov_b32_e32 v44, v156
	v_mov_b32_e32 v45, v157
	s_nop 1
	v_mov_b32_e32 v38, v212
	v_mov_b32_e32 v39, v213
	v_mov_b32_e32 v40, v214
	v_mov_b32_e32 v41, v215
	s_nop 1
	v_mov_b32_e32 v46, v158
	v_mov_b32_e32 v47, v159
	v_pk_fma_f32 v[16:17], v[16:17], v[34:35], v[42:43] op_sel_hi:[1,1,0]
	v_lshlrev_b32_e32 v34, 16, v44
	v_and_b32_e32 v35, 0xffff0000, v44
	v_pk_fma_f32 v[18:19], v[18:19], v[36:37], v[42:43] op_sel_hi:[1,1,0]
	v_lshlrev_b32_e32 v36, 16, v45
	v_and_b32_e32 v37, 0xffff0000, v45
	v_pk_fma_f32 v[20:21], v[20:21], v[38:39], v[42:43] op_sel_hi:[1,1,0]
	v_lshlrev_b32_e32 v38, 16, v46
	v_and_b32_e32 v39, 0xffff0000, v46
	v_pk_fma_f32 v[22:23], v[22:23], v[40:41], v[42:43] op_sel_hi:[1,1,0]
	v_lshlrev_b32_e32 v40, 16, v47
	v_and_b32_e32 v41, 0xffff0000, v47
	v_pk_mul_f32 v[16:17], v[16:17], v[34:35]
	v_pk_mul_f32 v[18:19], v[18:19], v[36:37]
	v_pk_mul_f32 v[20:21], v[20:21], v[38:39]
	v_pk_mul_f32 v[22:23], v[22:23], v[40:41]
	v_cvt_pk_bf16_f32 v16, v16, v17
	v_cvt_pk_bf16_f32 v17, v18, v19
	v_cvt_pk_bf16_f32 v18, v20, v21
	v_cvt_pk_bf16_f32 v19, v22, v23
	v_cndmask_b32_e64 v20, v17, v19, s[4:5]
	v_cndmask_b32_e64 v21, v16, v18, s[4:5]
	ds_bpermute_b32 v20, v117, v20
	ds_bpermute_b32 v21, v117, v21
	s_waitcnt lgkmcnt(1)
	v_cndmask_b32_e64 v19, v19, v20, s[4:5]
	v_cndmask_b32_e64 v17, v20, v17, s[4:5]
	s_waitcnt lgkmcnt(0)
; __device__ __forceinline__ unsigned pk2(float lo, float hi) { f32v2 v = {lo, hi}; bf16v2 r = __builtin_convertvector(v, bf16v2); return __builtin_bit_cast(unsigned, r); }
; __device__ __forceinline__ void gmlp_unit(const bf16* GVT, const bf16* U, const float* wsp, const float* bsp, const float* gain, bf16* OGM, int unit, LAS unsigned char* lds, int tid, int wave, int lane) {
;     ...
;             for (int gp = 0; gp < 2; ++gp) {
;                 v2u pc[2];
; #pragma unroll
;                 for (int e = 0; e < 2; ++e) { const int q4 = 2 * gp + e;
;                     const int c = g * 64 + mt * 32 + 8 * q4 + 4 * hh;
;                     const f32x4 gn = *(const f32x4*)(gain + c);
;                     const v2u uw = *(const v2u*)(U + (tok0 + t) * 256 + c);
;                     const float v0 = (acc[mt][nt][4 * q4] * gn.x + bias) * bf_lo(uw.x), v1 = (acc[mt][nt][4 * q4 + 1] * gn.y + bias) * bf_hi(uw.x);
;                     const float v2 = (acc[mt][nt][4 * q4 + 2] * gn.z + bias) * bf_lo(uw.y), v3 = (acc[mt][nt][4 * q4 + 3] * gn.w + bias) * bf_hi(uw.y);
;                     pc[e].x = pk2(v0, v1); pc[e].y = pk2(v2, v3); }
;                 *(v4u*)(OGM + (tok0 + t) * 256 + g * 64 + mt * 32 + 8 * (2 * gp + hh)) = pair_widen(pc[0], pc[1], hh);
;             }
;         }
;     __syncthreads();
	v_cndmask_b32_e64 v18, v18, v21, s[4:5]
	v_cndmask_b32_e64 v16, v21, v16, s[4:5]
	global_store_dwordx4 v[48:49], v[16:19], off offset:64 sc0 sc1
	s_nop 1
	v_mov_b32_e32 v16, v216
	v_mov_b32_e32 v17, v217
	v_mov_b32_e32 v18, v218
	v_mov_b32_e32 v19, v219
	s_nop 0
	s_nop 1
	v_mov_b32_e32 v34, v160
	v_mov_b32_e32 v35, v161
	s_nop 1
	v_mov_b32_e32 v20, v220
	v_mov_b32_e32 v21, v221
	v_mov_b32_e32 v22, v222
	v_mov_b32_e32 v23, v223
	s_nop 1
	v_mov_b32_e32 v36, v162
	v_mov_b32_e32 v37, v163
	v_pk_fma_f32 v[16:17], v[24:25], v[16:17], v[42:43] op_sel_hi:[1,1,0]
	v_lshlrev_b32_e32 v24, 16, v34
	v_and_b32_e32 v25, 0xffff0000, v34
	v_pk_fma_f32 v[18:19], v[26:27], v[18:19], v[42:43] op_sel_hi:[1,1,0]
	v_lshlrev_b32_e32 v26, 16, v35
	v_and_b32_e32 v27, 0xffff0000, v35
	v_pk_fma_f32 v[20:21], v[28:29], v[20:21], v[42:43] op_sel_hi:[1,1,0]
	v_lshlrev_b32_e32 v28, 16, v36
	v_and_b32_e32 v29, 0xffff0000, v36
	v_pk_fma_f32 v[22:23], v[30:31], v[22:23], v[42:43] op_sel_hi:[1,1,0]
	v_lshlrev_b32_e32 v30, 16, v37
	v_and_b32_e32 v31, 0xffff0000, v37
	v_pk_mul_f32 v[16:17], v[16:17], v[24:25]
	v_pk_mul_f32 v[18:19], v[18:19], v[26:27]
	v_pk_mul_f32 v[20:21], v[20:21], v[28:29]
	v_pk_mul_f32 v[22:23], v[22:23], v[30:31]
	v_cvt_pk_bf16_f32 v16, v16, v17
	v_cvt_pk_bf16_f32 v17, v18, v19
	v_cvt_pk_bf16_f32 v18, v20, v21
	v_cvt_pk_bf16_f32 v19, v22, v23
	v_cndmask_b32_e64 v20, v17, v19, s[4:5]
	v_cndmask_b32_e64 v21, v16, v18, s[4:5]
	ds_bpermute_b32 v20, v117, v20
	ds_bpermute_b32 v21, v117, v21
	s_waitcnt lgkmcnt(1)
	v_cndmask_b32_e64 v19, v19, v20, s[4:5]
	v_cndmask_b32_e64 v17, v20, v17, s[4:5]
	s_waitcnt lgkmcnt(0)
	v_cndmask_b32_e64 v18, v18, v21, s[4:5]
	v_cndmask_b32_e64 v16, v21, v16, s[4:5]
	global_store_dwordx4 v[48:49], v[16:19], off offset:96 sc0 sc1
	s_nop 1
	v_mov_b32_e32 v24, v181
	s_nop 0
	s_nop 1
	v_mov_b32_e32 v16, v208
	v_mov_b32_e32 v17, v209
	v_mov_b32_e32 v18, v210
	v_mov_b32_e32 v19, v211
	s_nop 1
	v_mov_b32_e32 v26, v240
	v_mov_b32_e32 v27, v241
	s_nop 1
	v_mov_b32_e32 v20, v212
	v_mov_b32_e32 v21, v213
	v_mov_b32_e32 v22, v214
	v_mov_b32_e32 v23, v215
	s_nop 1
	v_mov_b32_e32 v28, v242
	v_mov_b32_e32 v29, v243
	v_pk_fma_f32 v[0:1], v[0:1], v[16:17], v[24:25] op_sel_hi:[1,1,0]
	v_lshlrev_b32_e32 v16, 16, v26
	v_and_b32_e32 v17, 0xffff0000, v26
	v_pk_fma_f32 v[2:3], v[2:3], v[18:19], v[24:25] op_sel_hi:[1,1,0]
	v_lshlrev_b32_e32 v18, 16, v27
	v_and_b32_e32 v19, 0xffff0000, v27
	v_pk_fma_f32 v[4:5], v[4:5], v[20:21], v[24:25] op_sel_hi:[1,1,0]
	v_lshlrev_b32_e32 v20, 16, v28
	v_and_b32_e32 v21, 0xffff0000, v28
	v_pk_fma_f32 v[6:7], v[6:7], v[22:23], v[24:25] op_sel_hi:[1,1,0]
	v_lshlrev_b32_e32 v22, 16, v29
	v_and_b32_e32 v23, 0xffff0000, v29
	v_pk_mul_f32 v[0:1], v[0:1], v[16:17]
	v_pk_mul_f32 v[2:3], v[2:3], v[18:19]
	v_pk_mul_f32 v[4:5], v[4:5], v[20:21]
	v_pk_mul_f32 v[6:7], v[6:7], v[22:23]
	v_cvt_pk_bf16_f32 v0, v0, v1
	v_cvt_pk_bf16_f32 v1, v2, v3
	v_cvt_pk_bf16_f32 v2, v4, v5
	v_cvt_pk_bf16_f32 v3, v6, v7
	v_cndmask_b32_e64 v4, v1, v3, s[4:5]
	v_cndmask_b32_e64 v5, v0, v2, s[4:5]
	ds_bpermute_b32 v4, v117, v4
	ds_bpermute_b32 v5, v117, v5
	s_waitcnt lgkmcnt(1)
	v_cndmask_b32_e64 v3, v3, v4, s[4:5]
	v_cndmask_b32_e64 v1, v4, v1, s[4:5]
	s_waitcnt lgkmcnt(0)
	v_cndmask_b32_e64 v2, v2, v5, s[4:5]
	v_cndmask_b32_e64 v0, v5, v0, s[4:5]
	global_store_dwordx4 v[32:33], v[0:3], off offset:64 sc0 sc1
	s_nop 1
	v_mov_b32_e32 v0, v216
	v_mov_b32_e32 v1, v217
	v_mov_b32_e32 v2, v218
	v_mov_b32_e32 v3, v219
	s_nop 0
	s_nop 1
	v_mov_b32_e32 v16, v244
	v_mov_b32_e32 v17, v245
	s_nop 1
	v_mov_b32_e32 v4, v220
	v_mov_b32_e32 v5, v221
	v_mov_b32_e32 v6, v222
	v_mov_b32_e32 v7, v223
	s_nop 1
	v_mov_b32_e32 v18, v246
	v_mov_b32_e32 v19, v247
	v_pk_fma_f32 v[0:1], v[8:9], v[0:1], v[24:25] op_sel_hi:[1,1,0]
	v_lshlrev_b32_e32 v8, 16, v16
	v_and_b32_e32 v9, 0xffff0000, v16
	v_pk_fma_f32 v[2:3], v[10:11], v[2:3], v[24:25] op_sel_hi:[1,1,0]
	v_lshlrev_b32_e32 v10, 16, v17
	v_and_b32_e32 v11, 0xffff0000, v17
	v_pk_fma_f32 v[4:5], v[12:13], v[4:5], v[24:25] op_sel_hi:[1,1,0]
	v_lshlrev_b32_e32 v12, 16, v18
	v_and_b32_e32 v13, 0xffff0000, v18
	v_pk_fma_f32 v[6:7], v[14:15], v[6:7], v[24:25] op_sel_hi:[1,1,0]
	v_lshlrev_b32_e32 v14, 16, v19
	v_and_b32_e32 v15, 0xffff0000, v19
	v_pk_mul_f32 v[0:1], v[0:1], v[8:9]
	v_pk_mul_f32 v[2:3], v[2:3], v[10:11]
	v_pk_mul_f32 v[4:5], v[4:5], v[12:13]
	v_pk_mul_f32 v[6:7], v[6:7], v[14:15]
	v_cvt_pk_bf16_f32 v0, v0, v1
	v_cvt_pk_bf16_f32 v1, v2, v3
	v_cvt_pk_bf16_f32 v2, v4, v5
	v_cvt_pk_bf16_f32 v3, v6, v7
	v_cndmask_b32_e64 v4, v1, v3, s[4:5]
	v_cndmask_b32_e64 v5, v0, v2, s[4:5]
	ds_bpermute_b32 v4, v117, v4
	ds_bpermute_b32 v5, v117, v5
	s_waitcnt lgkmcnt(1)
	v_cndmask_b32_e64 v3, v3, v4, s[4:5]
	v_cndmask_b32_e64 v1, v4, v1, s[4:5]
	s_waitcnt lgkmcnt(0)
	v_cndmask_b32_e64 v2, v2, v5, s[4:5]
	v_cndmask_b32_e64 v0, v5, v0, s[4:5]
	global_store_dwordx4 v[32:33], v[0:3], off offset:96 sc0 sc1
	s_barrier
	s_cbranch_scc0 .LBB0_102

; __device__ __forceinline__ unsigned pk2(float lo, float hi) { f32v2 v = {lo, hi}; bf16v2 r = __builtin_convertvector(v, bf16v2); return __builtin_bit_cast(unsigned, r); }
; __device__ __forceinline__ void attn_unit(const bf16* Q, const bf16* Kb, const bf16* VT, bf16* OSB, int wu, int lane) {
;     ...
;     bf16* op = OSB + (tok0 + r) * 512 + h * 64;
; #pragma unroll
;     for (int mt = 0; mt < 2; ++mt)
; #pragma unroll
;         for (int gp = 0; gp < 2; ++gp) {
;             const int g0 = 2 * gp, g1 = 2 * gp + 1;
;             unsigned a0w, a1w, b0w, b1w;
;             if (mt == 0) { a0w = pk2(o0[4 * g0], o0[4 * g0 + 1]); a1w = pk2(o0[4 * g0 + 2], o0[4 * g0 + 3]); b0w = pk2(o0[4 * g1], o0[4 * g1 + 1]); b1w = pk2(o0[4 * g1 + 2], o0[4 * g1 + 3]); }
;             else         { a0w = pk2(o1[4 * g0], o1[4 * g0 + 1]); a1w = pk2(o1[4 * g0 + 2], o1[4 * g0 + 3]); b0w = pk2(o1[4 * g1], o1[4 * g1 + 1]); b1w = pk2(o1[4 * g1 + 2], o1[4 * g1 + 3]); }
;             const unsigned s0 = hh ? a0w : b0w, s1 = hh ? a1w : b1w;
;             const unsigned r0 = (unsigned)__shfl_xor((int)s0, 32), r1 = (unsigned)__shfl_xor((int)s1, 32);
;             v4u w; if (hh == 0) { w.x = a0w; w.y = a1w; w.z = r0; w.w = r1; } else { w.x = r0; w.y = r1; w.z = b0w; w.w = b1w; }
;             *(v4u*)(op + mt * 32 + 8 * (hh ? g1 : g0)) = w;
;         }
; __global__ void __launch_bounds__(NTHREADS, 2) fwd_megakernel(Args A) {
;     ...
;             for (int wu = gw; wu < 8192 + 4096; wu += ngw) {
;                 if (wu < 8192) attn_unit(Qb, Kb, VT, OSB, wu, lane);
;                 else pool_unit(P, WB + WO_WPT, OPOOL, wu - 8192, lane);
;             }
.LBB0_109:
	s_nop 6
	v_cvt_pk_bf16_f32 v22, v22, v23
	v_cvt_pk_bf16_f32 v20, v20, v21
	v_cvt_pk_bf16_f32 v21, v18, v19
	v_cvt_pk_bf16_f32 v23, v16, v17
	v_cndmask_b32_e64 v16, v20, v23, s[4:5]
	v_cndmask_b32_e64 v17, v22, v21, s[4:5]
	ds_bpermute_b32 v34, v73, v17
	ds_bpermute_b32 v35, v73, v16
	v_lshlrev_b64 v[32:33], 9, v[96:97]
	v_lshl_add_u64 v[16:17], v[32:33], 1, s[70:71]
	s_mov_b32 s47, s95
	v_lshl_add_u64 v[32:33], v[16:17], 0, s[46:47]
	s_waitcnt lgkmcnt(1)
	v_cndmask_b32_e64 v19, v34, v22, s[4:5]
	s_waitcnt lgkmcnt(0)
	v_cndmask_b32_e64 v16, v23, v35, s[4:5]
	v_cvt_pk_bf16_f32 v22, v30, v31
	v_cvt_pk_bf16_f32 v23, v28, v29
	v_cvt_pk_bf16_f32 v26, v26, v27
	v_cvt_pk_bf16_f32 v24, v24, v25
	v_cndmask_b32_e64 v18, v35, v20, s[4:5]
	v_cndmask_b32_e64 v17, v21, v34, s[4:5]
	v_cndmask_b32_e64 v20, v23, v24, s[4:5]
	v_cndmask_b32_e64 v21, v22, v26, s[4:5]
	ds_bpermute_b32 v25, v73, v21
	ds_bpermute_b32 v27, v73, v20
	v_lshlrev_b32_e32 v178, 1, v72
	v_cvt_pk_bf16_f32 v6, v6, v7
	v_cvt_pk_bf16_f32 v4, v4, v5
	v_cvt_pk_bf16_f32 v5, v2, v3
	v_cvt_pk_bf16_f32 v7, v0, v1
	v_lshl_add_u64 v[20:21], v[32:33], 0, v[178:179]
	v_cndmask_b32_e64 v0, v4, v7, s[4:5]
	v_cndmask_b32_e64 v1, v6, v5, s[4:5]
	global_store_dwordx4 v[20:21], v[16:19], off sc0 sc1
	v_lshlrev_b32_e32 v178, 1, v74
	v_cvt_pk_bf16_f32 v10, v10, v11
	s_waitcnt lgkmcnt(1)
	v_cndmask_b32_e64 v19, v25, v22, s[4:5]
	s_waitcnt lgkmcnt(0)
	v_cndmask_b32_e64 v18, v27, v23, s[4:5]
	ds_bpermute_b32 v22, v73, v1
	ds_bpermute_b32 v23, v73, v0
	v_cndmask_b32_e64 v17, v26, v25, s[4:5]
	v_cndmask_b32_e64 v16, v24, v27, s[4:5]
	v_lshl_add_u64 v[0:1], v[32:33], 0, v[178:179]
	s_waitcnt lgkmcnt(1)
	v_cndmask_b32_e64 v3, v22, v6, s[4:5]
	s_waitcnt lgkmcnt(0)
	v_cndmask_b32_e64 v2, v23, v4, s[4:5]
	v_cvt_pk_bf16_f32 v4, v14, v15
	v_cvt_pk_bf16_f32 v6, v12, v13
	v_cvt_pk_bf16_f32 v8, v8, v9
	global_store_dwordx4 v[0:1], v[16:19], off sc0 sc1
	v_cndmask_b32_e64 v0, v6, v8, s[4:5]
	v_cndmask_b32_e64 v1, v4, v10, s[4:5]
	ds_bpermute_b32 v9, v73, v1
	ds_bpermute_b32 v11, v73, v0
	v_cndmask_b32_e64 v1, v5, v22, s[4:5]
	v_cndmask_b32_e64 v0, v7, v23, s[4:5]
	global_store_dwordx4 v[20:21], v[0:3], off offset:64 sc0 sc1
	s_waitcnt lgkmcnt(1)
	s_nop 0
	v_cndmask_b32_e64 v3, v9, v4, s[4:5]
	s_waitcnt lgkmcnt(0)
	v_cndmask_b32_e64 v2, v11, v6, s[4:5]
	v_cndmask_b32_e64 v1, v10, v9, s[4:5]
	v_cndmask_b32_e64 v0, v8, v11, s[4:5]
.LBB0_110:
	v_lshlrev_b32_e32 v178, 1, v74
	s_add_i32 s96, s96, s66
	v_lshl_add_u64 v[4:5], v[32:33], 0, v[178:179]
	s_cmpk_gt_i32 s96, 0x2fff
	global_store_dwordx4 v[4:5], v[0:3], off offset:64 sc0 sc1
	s_cbranch_scc1 .LBB0_121

; #define PL_UNPACK(dst0, dst1, w_) do { dst0 = (f32x4){bf_lo((w_).x), bf_hi((w_).x), bf_lo((w_).y), bf_hi((w_).y)}; dst1 = (f32x4){bf_lo((w_).z), bf_hi((w_).z), bf_lo((w_).w), bf_hi((w_).w)}; } while (0)
; __device__ __forceinline__ void pool_unit(const float* P, const bf16* WPT, bf16* OPOOL, int pu, int lane) {
;     ...
;     for (int j = 1; j < w; ++j) {
;         const bool ok = j <= tl; const float wg = ok ? 1.f : 0.f; const bf16* q = pp - (size_t)(ok ? j : 0) * 256;
; #pragma unroll
;         for (int kk = 0; kk < 4; ++kk) { const v4u w_ = *(const v4u*)(q + kk * 16); f32x4 a_, b_; PL_UNPACK(a_, b_, w_); s[kk][0] += wg * a_; s[kk][1] += wg * b_; }
;     }
.LBB0_113:
	v_mov_b32_e32 v23, s41
	v_cmp_gt_u32_e32 vcc, s41, v22
	v_cndmask_b32_e64 v23, v23, 0, vcc
	v_cndmask_b32_e64 v156, 1.0, 0, vcc
	v_mad_u64_u32 v[148:149], s[42:43], v23, s0, v[8:9]
	v_sub_u32_e32 v149, v149, v23
	global_load_dwordx4 v[160:163], v[148:149], off
	global_load_dwordx4 v[164:167], v[148:149], off offset:32
	global_load_dwordx4 v[168:171], v[148:149], off offset:64
	global_load_dwordx4 v[172:175], v[148:149], off offset:96
	s_add_i32 s42, s41, 1
	v_mov_b32_e32 v23, s42
	v_cmp_gt_u32_e32 vcc, s42, v22
	v_cndmask_b32_e64 v23, v23, 0, vcc
	v_cndmask_b32_e64 v158, 1.0, 0, vcc
	v_mad_u64_u32 v[150:151], s[42:43], v23, s0, v[8:9]
	v_sub_u32_e32 v151, v151, v23
	global_load_dwordx4 v[192:195], v[150:151], off
	global_load_dwordx4 v[196:199], v[150:151], off offset:32
	global_load_dwordx4 v[200:203], v[150:151], off offset:64
	global_load_dwordx4 v[204:207], v[150:151], off offset:96
	s_add_i32 s42, s41, 2
	v_mov_b32_e32 v23, s42
	v_cmp_gt_u32_e32 vcc, s42, v22
	v_cndmask_b32_e64 v23, v23, 0, vcc
	v_cndmask_b32_e64 v180, 1.0, 0, vcc
	v_mad_u64_u32 v[152:153], s[42:43], v23, s0, v[8:9]
	v_sub_u32_e32 v153, v153, v23
	global_load_dwordx4 v[208:211], v[152:153], off
	global_load_dwordx4 v[212:215], v[152:153], off offset:32
	global_load_dwordx4 v[216:219], v[152:153], off offset:64
	global_load_dwordx4 v[220:223], v[152:153], off offset:96
	s_add_i32 s42, s41, 3
	v_mov_b32_e32 v23, s42
	v_cmp_gt_u32_e32 vcc, s42, v22
	v_cndmask_b32_e64 v23, v23, 0, vcc
	v_cndmask_b32_e64 v182, 1.0, 0, vcc
	v_mad_u64_u32 v[154:155], s[42:43], v23, s0, v[8:9]
	v_sub_u32_e32 v155, v155, v23
	global_load_dwordx4 v[232:235], v[154:155], off
	global_load_dwordx4 v[236:239], v[154:155], off offset:32
	global_load_dwordx4 v[240:243], v[154:155], off offset:64
	global_load_dwordx4 v[244:247], v[154:155], off offset:96
	s_waitcnt vmcnt(12)
	v_lshlrev_b32_e32 v112, 16, v160
	v_and_b32_e32 v113, 0xffff0000, v160
	v_lshlrev_b32_e32 v24, 16, v161
	v_and_b32_e32 v25, 0xffff0000, v161
	v_lshlrev_b32_e32 v114, 16, v162
	v_and_b32_e32 v115, 0xffff0000, v162
	v_lshlrev_b32_e32 v26, 16, v163
	v_and_b32_e32 v27, 0xffff0000, v163
	v_lshlrev_b32_e32 v116, 16, v164
	v_and_b32_e32 v117, 0xffff0000, v164
	v_lshlrev_b32_e32 v28, 16, v165
	v_and_b32_e32 v29, 0xffff0000, v165
	v_lshlrev_b32_e32 v118, 16, v166
	v_and_b32_e32 v119, 0xffff0000, v166
	v_lshlrev_b32_e32 v30, 16, v167
	v_and_b32_e32 v31, 0xffff0000, v167
	v_lshlrev_b32_e32 v120, 16, v168
	v_and_b32_e32 v121, 0xffff0000, v168
	v_lshlrev_b32_e32 v102, 16, v169
	v_and_b32_e32 v103, 0xffff0000, v169
	v_lshlrev_b32_e32 v122, 16, v170
	v_and_b32_e32 v123, 0xffff0000, v170
	v_lshlrev_b32_e32 v104, 16, v171
	v_and_b32_e32 v105, 0xffff0000, v171
	v_lshlrev_b32_e32 v124, 16, v172
	v_and_b32_e32 v125, 0xffff0000, v172
	v_lshlrev_b32_e32 v106, 16, v173
	v_and_b32_e32 v107, 0xffff0000, v173
	v_lshlrev_b32_e32 v126, 16, v174
	v_and_b32_e32 v127, 0xffff0000, v174
	v_lshlrev_b32_e32 v108, 16, v175
	v_and_b32_e32 v109, 0xffff0000, v175
	v_pk_fma_f32 v[10:11], v[156:157], v[24:25], v[10:11] op_sel_hi:[0,1,1]
	v_pk_fma_f32 v[12:13], v[156:157], v[112:113], v[12:13] op_sel_hi:[0,1,1]
	v_pk_fma_f32 v[14:15], v[156:157], v[26:27], v[14:15] op_sel_hi:[0,1,1]
	v_pk_fma_f32 v[20:21], v[156:157], v[114:115], v[20:21] op_sel_hi:[0,1,1]
	v_pk_fma_f32 v[96:97], v[156:157], v[28:29], v[96:97] op_sel_hi:[0,1,1]
	v_pk_fma_f32 v[18:19], v[156:157], v[116:117], v[18:19] op_sel_hi:[0,1,1]
	v_pk_fma_f32 v[98:99], v[156:157], v[30:31], v[98:99] op_sel_hi:[0,1,1]
	v_pk_fma_f32 v[100:101], v[156:157], v[118:119], v[100:101] op_sel_hi:[0,1,1]
	v_pk_fma_f32 v[58:59], v[156:157], v[102:103], v[58:59] op_sel_hi:[0,1,1]
	v_pk_fma_f32 v[60:61], v[156:157], v[120:121], v[60:61] op_sel_hi:[0,1,1]
	v_pk_fma_f32 v[62:63], v[156:157], v[104:105], v[62:63] op_sel_hi:[0,1,1]
	v_pk_fma_f32 v[64:65], v[156:157], v[122:123], v[64:65] op_sel_hi:[0,1,1]
	v_pk_fma_f32 v[50:51], v[156:157], v[106:107], v[50:51] op_sel_hi:[0,1,1]
	v_pk_fma_f32 v[52:53], v[156:157], v[124:125], v[52:53] op_sel_hi:[0,1,1]
	v_pk_fma_f32 v[54:55], v[156:157], v[108:109], v[54:55] op_sel_hi:[0,1,1]
	v_pk_fma_f32 v[56:57], v[156:157], v[126:127], v[56:57] op_sel_hi:[0,1,1]
	s_waitcnt vmcnt(8)
	v_lshlrev_b32_e32 v112, 16, v192
	v_and_b32_e32 v113, 0xffff0000, v192
	v_lshlrev_b32_e32 v24, 16, v193
	v_and_b32_e32 v25, 0xffff0000, v193
	v_lshlrev_b32_e32 v114, 16, v194
	v_and_b32_e32 v115, 0xffff0000, v194
	v_lshlrev_b32_e32 v26, 16, v195
	v_and_b32_e32 v27, 0xffff0000, v195
	v_lshlrev_b32_e32 v116, 16, v196
	v_and_b32_e32 v117, 0xffff0000, v196
	v_lshlrev_b32_e32 v28, 16, v197
	v_and_b32_e32 v29, 0xffff0000, v197
	v_lshlrev_b32_e32 v118, 16, v198
	v_and_b32_e32 v119, 0xffff0000, v198
	v_lshlrev_b32_e32 v30, 16, v199
	v_and_b32_e32 v31, 0xffff0000, v199
	v_lshlrev_b32_e32 v120, 16, v200
	v_and_b32_e32 v121, 0xffff0000, v200
	v_lshlrev_b32_e32 v102, 16, v201
	v_and_b32_e32 v103, 0xffff0000, v201
	v_lshlrev_b32_e32 v122, 16, v202
	v_and_b32_e32 v123, 0xffff0000, v202
	v_lshlrev_b32_e32 v104, 16, v203
	v_and_b32_e32 v105, 0xffff0000, v203
	v_lshlrev_b32_e32 v124, 16, v204
	v_and_b32_e32 v125, 0xffff0000, v204
	v_lshlrev_b32_e32 v106, 16, v205
	v_and_b32_e32 v107, 0xffff0000, v205
	v_lshlrev_b32_e32 v126, 16, v206
	v_and_b32_e32 v127, 0xffff0000, v206
	v_lshlrev_b32_e32 v108, 16, v207
	v_and_b32_e32 v109, 0xffff0000, v207
	v_pk_fma_f32 v[10:11], v[158:159], v[24:25], v[10:11] op_sel_hi:[0,1,1]
	v_pk_fma_f32 v[12:13], v[158:159], v[112:113], v[12:13] op_sel_hi:[0,1,1]
	v_pk_fma_f32 v[14:15], v[158:159], v[26:27], v[14:15] op_sel_hi:[0,1,1]
	v_pk_fma_f32 v[20:21], v[158:159], v[114:115], v[20:21] op_sel_hi:[0,1,1]
	v_pk_fma_f32 v[96:97], v[158:159], v[28:29], v[96:97] op_sel_hi:[0,1,1]
	v_pk_fma_f32 v[18:19], v[158:159], v[116:117], v[18:19] op_sel_hi:[0,1,1]
	v_pk_fma_f32 v[98:99], v[158:159], v[30:31], v[98:99] op_sel_hi:[0,1,1]
	v_pk_fma_f32 v[100:101], v[158:159], v[118:119], v[100:101] op_sel_hi:[0,1,1]
	v_pk_fma_f32 v[58:59], v[158:159], v[102:103], v[58:59] op_sel_hi:[0,1,1]
	v_pk_fma_f32 v[60:61], v[158:159], v[120:121], v[60:61] op_sel_hi:[0,1,1]
	v_pk_fma_f32 v[62:63], v[158:159], v[104:105], v[62:63] op_sel_hi:[0,1,1]
	v_pk_fma_f32 v[64:65], v[158:159], v[122:123], v[64:65] op_sel_hi:[0,1,1]
	v_pk_fma_f32 v[50:51], v[158:159], v[106:107], v[50:51] op_sel_hi:[0,1,1]
	v_pk_fma_f32 v[52:53], v[158:159], v[124:125], v[52:53] op_sel_hi:[0,1,1]
	v_pk_fma_f32 v[54:55], v[158:159], v[108:109], v[54:55] op_sel_hi:[0,1,1]
	v_pk_fma_f32 v[56:57], v[158:159], v[126:127], v[56:57] op_sel_hi:[0,1,1]
	s_waitcnt vmcnt(4)
; #define PL_UNPACK(dst0, dst1, w_) do { dst0 = (f32x4){bf_lo((w_).x), bf_hi((w_).x), bf_lo((w_).y), bf_hi((w_).y)}; dst1 = (f32x4){bf_lo((w_).z), bf_hi((w_).z), bf_lo((w_).w), bf_hi((w_).w)}; } while (0)
; __device__ __forceinline__ void pool_unit(const float* P, const bf16* WPT, bf16* OPOOL, int pu, int lane) {
;     ...
;     for (int j = 1; j < w; ++j) {
;         const bool ok = j <= tl; const float wg = ok ? 1.f : 0.f; const bf16* q = pp - (size_t)(ok ? j : 0) * 256;
; #pragma unroll
;         for (int kk = 0; kk < 4; ++kk) { const v4u w_ = *(const v4u*)(q + kk * 16); f32x4 a_, b_; PL_UNPACK(a_, b_, w_); s[kk][0] += wg * a_; s[kk][1] += wg * b_; }
;     }
	v_lshlrev_b32_e32 v112, 16, v208
	v_and_b32_e32 v113, 0xffff0000, v208
	v_lshlrev_b32_e32 v24, 16, v209
	v_and_b32_e32 v25, 0xffff0000, v209
	v_lshlrev_b32_e32 v114, 16, v210
	v_and_b32_e32 v115, 0xffff0000, v210
	v_lshlrev_b32_e32 v26, 16, v211
	v_and_b32_e32 v27, 0xffff0000, v211
	v_lshlrev_b32_e32 v116, 16, v212
	v_and_b32_e32 v117, 0xffff0000, v212
	v_lshlrev_b32_e32 v28, 16, v213
	v_and_b32_e32 v29, 0xffff0000, v213
	v_lshlrev_b32_e32 v118, 16, v214
	v_and_b32_e32 v119, 0xffff0000, v214
	v_lshlrev_b32_e32 v30, 16, v215
	v_and_b32_e32 v31, 0xffff0000, v215
	v_lshlrev_b32_e32 v120, 16, v216
	v_and_b32_e32 v121, 0xffff0000, v216
	v_lshlrev_b32_e32 v102, 16, v217
	v_and_b32_e32 v103, 0xffff0000, v217
	v_lshlrev_b32_e32 v122, 16, v218
	v_and_b32_e32 v123, 0xffff0000, v218
	v_lshlrev_b32_e32 v104, 16, v219
	v_and_b32_e32 v105, 0xffff0000, v219
	v_lshlrev_b32_e32 v124, 16, v220
	v_and_b32_e32 v125, 0xffff0000, v220
	v_lshlrev_b32_e32 v106, 16, v221
	v_and_b32_e32 v107, 0xffff0000, v221
	v_lshlrev_b32_e32 v126, 16, v222
	v_and_b32_e32 v127, 0xffff0000, v222
	v_lshlrev_b32_e32 v108, 16, v223
	v_and_b32_e32 v109, 0xffff0000, v223
	v_pk_fma_f32 v[10:11], v[180:181], v[24:25], v[10:11] op_sel_hi:[0,1,1]
	v_pk_fma_f32 v[12:13], v[180:181], v[112:113], v[12:13] op_sel_hi:[0,1,1]
	v_pk_fma_f32 v[14:15], v[180:181], v[26:27], v[14:15] op_sel_hi:[0,1,1]
	v_pk_fma_f32 v[20:21], v[180:181], v[114:115], v[20:21] op_sel_hi:[0,1,1]
	v_pk_fma_f32 v[96:97], v[180:181], v[28:29], v[96:97] op_sel_hi:[0,1,1]
	v_pk_fma_f32 v[18:19], v[180:181], v[116:117], v[18:19] op_sel_hi:[0,1,1]
	v_pk_fma_f32 v[98:99], v[180:181], v[30:31], v[98:99] op_sel_hi:[0,1,1]
	v_pk_fma_f32 v[100:101], v[180:181], v[118:119], v[100:101] op_sel_hi:[0,1,1]
	v_pk_fma_f32 v[58:59], v[180:181], v[102:103], v[58:59] op_sel_hi:[0,1,1]
	v_pk_fma_f32 v[60:61], v[180:181], v[120:121], v[60:61] op_sel_hi:[0,1,1]
	v_pk_fma_f32 v[62:63], v[180:181], v[104:105], v[62:63] op_sel_hi:[0,1,1]
	v_pk_fma_f32 v[64:65], v[180:181], v[122:123], v[64:65] op_sel_hi:[0,1,1]
	v_pk_fma_f32 v[50:51], v[180:181], v[106:107], v[50:51] op_sel_hi:[0,1,1]
	v_pk_fma_f32 v[52:53], v[180:181], v[124:125], v[52:53] op_sel_hi:[0,1,1]
	v_pk_fma_f32 v[54:55], v[180:181], v[108:109], v[54:55] op_sel_hi:[0,1,1]
	v_pk_fma_f32 v[56:57], v[180:181], v[126:127], v[56:57] op_sel_hi:[0,1,1]
	s_waitcnt vmcnt(0)
	v_lshlrev_b32_e32 v112, 16, v232
	v_and_b32_e32 v113, 0xffff0000, v232
	v_lshlrev_b32_e32 v24, 16, v233
	v_and_b32_e32 v25, 0xffff0000, v233
	v_lshlrev_b32_e32 v114, 16, v234
	v_and_b32_e32 v115, 0xffff0000, v234
	v_lshlrev_b32_e32 v26, 16, v235
	v_and_b32_e32 v27, 0xffff0000, v235
	v_lshlrev_b32_e32 v116, 16, v236
	v_and_b32_e32 v117, 0xffff0000, v236
	v_lshlrev_b32_e32 v28, 16, v237
	v_and_b32_e32 v29, 0xffff0000, v237
	v_lshlrev_b32_e32 v118, 16, v238
	v_and_b32_e32 v119, 0xffff0000, v238
	v_lshlrev_b32_e32 v30, 16, v239
	v_and_b32_e32 v31, 0xffff0000, v239
	v_lshlrev_b32_e32 v120, 16, v240
	v_and_b32_e32 v121, 0xffff0000, v240
	v_lshlrev_b32_e32 v102, 16, v241
	v_and_b32_e32 v103, 0xffff0000, v241
	v_lshlrev_b32_e32 v122, 16, v242
	v_and_b32_e32 v123, 0xffff0000, v242
	v_lshlrev_b32_e32 v104, 16, v243
	v_and_b32_e32 v105, 0xffff0000, v243
	v_lshlrev_b32_e32 v124, 16, v244
	v_and_b32_e32 v125, 0xffff0000, v244
	v_lshlrev_b32_e32 v106, 16, v245
	v_and_b32_e32 v107, 0xffff0000, v245
	v_lshlrev_b32_e32 v126, 16, v246
	v_and_b32_e32 v127, 0xffff0000, v246
	v_lshlrev_b32_e32 v108, 16, v247
	v_and_b32_e32 v109, 0xffff0000, v247
	v_pk_fma_f32 v[10:11], v[182:183], v[24:25], v[10:11] op_sel_hi:[0,1,1]
	v_pk_fma_f32 v[12:13], v[182:183], v[112:113], v[12:13] op_sel_hi:[0,1,1]
	v_pk_fma_f32 v[14:15], v[182:183], v[26:27], v[14:15] op_sel_hi:[0,1,1]
	v_pk_fma_f32 v[20:21], v[182:183], v[114:115], v[20:21] op_sel_hi:[0,1,1]
	v_pk_fma_f32 v[96:97], v[182:183], v[28:29], v[96:97] op_sel_hi:[0,1,1]
	v_pk_fma_f32 v[18:19], v[182:183], v[116:117], v[18:19] op_sel_hi:[0,1,1]
	v_pk_fma_f32 v[98:99], v[182:183], v[30:31], v[98:99] op_sel_hi:[0,1,1]
	v_pk_fma_f32 v[100:101], v[182:183], v[118:119], v[100:101] op_sel_hi:[0,1,1]
	v_pk_fma_f32 v[58:59], v[182:183], v[102:103], v[58:59] op_sel_hi:[0,1,1]
	v_pk_fma_f32 v[60:61], v[182:183], v[120:121], v[60:61] op_sel_hi:[0,1,1]
	v_pk_fma_f32 v[62:63], v[182:183], v[104:105], v[62:63] op_sel_hi:[0,1,1]
	v_pk_fma_f32 v[64:65], v[182:183], v[122:123], v[64:65] op_sel_hi:[0,1,1]
	v_pk_fma_f32 v[50:51], v[182:183], v[106:107], v[50:51] op_sel_hi:[0,1,1]
	v_pk_fma_f32 v[52:53], v[182:183], v[124:125], v[52:53] op_sel_hi:[0,1,1]
	v_pk_fma_f32 v[54:55], v[182:183], v[108:109], v[54:55] op_sel_hi:[0,1,1]
	v_pk_fma_f32 v[56:57], v[182:183], v[126:127], v[56:57] op_sel_hi:[0,1,1]
	s_add_i32 s41, s41, 4
	s_cmp_lt_u32 s41, s40
	s_cbranch_scc1 .LBB0_113
; __device__ __forceinline__ unsigned pk2(float lo, float hi) { f32v2 v = {lo, hi}; bf16v2 r = __builtin_convertvector(v, bf16v2); return __builtin_bit_cast(unsigned, r); }
; #define MFMA32(a, b, c) __builtin_amdgcn_mfma_f32_32x32x16_bf16((a), (b), (c), 0, 0, 0)
; __device__ __forceinline__ void pool_unit(const float* P, const bf16* WPT, bf16* OPOOL, int pu, int lane) {
;     ...
;     const float inv = 1.0f / (float)(tl + 1 < w ? tl + 1 : w);
;     f32x16 acc0, acc1;
; #pragma unroll
;     for (int i = 0; i < 16; ++i) { acc0[i] = 0.f; acc1[i] = 0.f; }
;     const bf16* wp = WPT + (size_t)(g * 64 + r) * 64 + 8 * hh;
; #pragma unroll
;     for (int kk = 0; kk < 4; ++kk) {
;         float a[8];
; #pragma unroll
;         for (int e = 0; e < 4; ++e) { a[e] = s[kk][0][e] * inv - p0[kk][0][e]; a[4 + e] = s[kk][1][e] * inv - p0[kk][1][e]; }
;         const bf16x8 pf = pack8(a);
;         acc0 = MFMA32(*(const bf16x8*)(wp + kk * 16), pf, acc0);
;         acc1 = MFMA32(*(const bf16x8*)(wp + 32 * 64 + kk * 16), pf, acc1);
;     }
;     bf16* op = OPOOL + (size_t)tok * 256 + g * 64;
; #pragma unroll
;     for (int gp = 0; gp < 2; ++gp) {
;         const int g0 = 2 * gp, g1 = 2 * gp + 1;
;         v2u a, b;
;         a.x = pk2(acc0[4 * g0], acc0[4 * g0 + 1]); a.y = pk2(acc0[4 * g0 + 2], acc0[4 * g0 + 3]); b.x = pk2(acc0[4 * g1], acc0[4 * g1 + 1]); b.y = pk2(acc0[4 * g1 + 2], acc0[4 * g1 + 3]);
;         *(v4u*)(op + 8 * (hh ? g1 : g0)) = pair_widen(a, b, hh);
;         a.x = pk2(acc1[4 * g0], acc1[4 * g0 + 1]); a.y = pk2(acc1[4 * g0 + 2], acc1[4 * g0 + 3]); b.x = pk2(acc1[4 * g1], acc1[4 * g1 + 1]); b.y = pk2(acc1[4 * g1 + 2], acc1[4 * g1 + 3]);
;         *(v4u*)(op + 32 + 8 * (hh ? g1 : g0)) = pair_widen(a, b, hh);
	global_load_dwordx4 v[24:27], v[82:83], off
	global_load_dwordx4 v[28:31], v[84:85], off
	global_load_dwordx4 v[102:105], v[82:83], off offset:32
	v_add_u32_e32 v8, 1, v22
	v_min_u32_e32 v8, s40, v8
	v_cvt_f32_ubyte0_e32 v8, v8
	v_div_scale_f32 v9, s[42:43], v8, v8, 1.0
	v_rcp_f32_e32 v22, v9
	v_div_scale_f32 v23, vcc, 1.0, v8, 1.0
	global_load_dwordx4 v[106:109], v[88:89], off
	global_load_dwordx4 v[110:113], v[82:83], off offset:64
	v_fma_f32 v33, -v9, v22, 1.0
	v_fmac_f32_e32 v22, v33, v22
	v_mul_f32_e32 v33, v23, v22
	v_fma_f32 v73, -v9, v33, v23
	v_fmac_f32_e32 v33, v73, v22
	v_fma_f32 v9, -v9, v33, v23
	v_div_fmas_f32 v9, v9, v22, v33
	v_div_fixup_f32 v114, v9, v8, 1.0
	v_pk_fma_f32 v[2:3], v[114:115], v[12:13], v[2:3] op_sel_hi:[0,1,1] neg_lo:[0,0,1] neg_hi:[0,0,1]
	v_pk_fma_f32 v[6:7], v[114:115], v[20:21], v[6:7] op_sel_hi:[0,1,1] neg_lo:[0,0,1] neg_hi:[0,0,1]
	v_pk_fma_f32 v[0:1], v[114:115], v[10:11], v[0:1] op_sel_hi:[0,1,1] neg_lo:[0,0,1] neg_hi:[0,0,1]
	v_pk_fma_f32 v[4:5], v[114:115], v[14:15], v[4:5] op_sel_hi:[0,1,1] neg_lo:[0,0,1] neg_hi:[0,0,1]
	v_cvt_pk_bf16_f32 v20, v2, v3
	v_cvt_pk_bf16_f32 v21, v0, v1
	v_cvt_pk_bf16_f32 v22, v6, v7
	v_cvt_pk_bf16_f32 v23, v4, v5
	v_pk_fma_f32 v[116:117], v[114:115], v[18:19], v[16:17] op_sel_hi:[0,1,1] neg_lo:[0,0,1] neg_hi:[0,0,1]
	v_pk_fma_f32 v[70:71], v[114:115], v[100:101], v[70:71] op_sel_hi:[0,1,1] neg_lo:[0,0,1] neg_hi:[0,0,1]
	v_pk_fma_f32 v[96:97], v[114:115], v[96:97], v[66:67] op_sel_hi:[0,1,1] neg_lo:[0,0,1] neg_hi:[0,0,1]
	v_pk_fma_f32 v[98:99], v[114:115], v[98:99], v[68:69] op_sel_hi:[0,1,1] neg_lo:[0,0,1] neg_hi:[0,0,1]
	v_cvt_pk_bf16_f32 v66, v116, v117
	v_cvt_pk_bf16_f32 v67, v96, v97
	v_cvt_pk_bf16_f32 v68, v70, v71
	v_cvt_pk_bf16_f32 v69, v98, v99
	v_pk_fma_f32 v[44:45], v[114:115], v[60:61], v[44:45] op_sel_hi:[0,1,1] neg_lo:[0,0,1] neg_hi:[0,0,1]
	v_pk_fma_f32 v[48:49], v[114:115], v[64:65], v[48:49] op_sel_hi:[0,1,1] neg_lo:[0,0,1] neg_hi:[0,0,1]
	v_pk_fma_f32 v[46:47], v[114:115], v[62:63], v[46:47] op_sel_hi:[0,1,1] neg_lo:[0,0,1] neg_hi:[0,0,1]
	v_pk_fma_f32 v[58:59], v[114:115], v[58:59], v[42:43] op_sel_hi:[0,1,1] neg_lo:[0,0,1] neg_hi:[0,0,1]
	v_cvt_pk_bf16_f32 v42, v44, v45
	v_cvt_pk_bf16_f32 v44, v48, v49
	v_cvt_pk_bf16_f32 v45, v46, v47
	v_cvt_pk_bf16_f32 v43, v58, v59
	v_pk_fma_f32 v[36:37], v[114:115], v[52:53], v[36:37] op_sel_hi:[0,1,1] neg_lo:[0,0,1] neg_hi:[0,0,1]
	v_pk_fma_f32 v[40:41], v[114:115], v[56:57], v[40:41] op_sel_hi:[0,1,1] neg_lo:[0,0,1] neg_hi:[0,0,1]
	v_pk_fma_f32 v[38:39], v[114:115], v[54:55], v[38:39] op_sel_hi:[0,1,1] neg_lo:[0,0,1] neg_hi:[0,0,1]
	v_and_b32_e32 v59, 64, v226
	v_xor_b32_e32 v58, 32, v226
	v_add_u32_e32 v59, 64, v59
	v_cmp_lt_i32_e32 vcc, v58, v59
	v_lshlrev_b32_e32 v178, 1, v32
	v_lshl_add_u64 v[32:33], s[60:61], 0, v[178:179]
	v_lshlrev_b32_e32 v178, 1, v72
	s_mov_b64 s[46:47], 0
	s_waitcnt vmcnt(0)
	v_mfma_f32_32x32x16_bf16 v[0:15], v[24:27], v[20:23], 0
	s_waitcnt vmcnt(2)
	v_mfma_f32_32x32x16_bf16 v[0:15], v[102:105], v[66:69], v[0:15]
	global_load_dwordx4 v[96:99], v[90:91], off
	global_load_dwordx4 v[100:103], v[82:83], off offset:96
	global_load_dwordx4 v[46:49], v[92:93], off
	v_mfma_f32_32x32x16_bf16 v[16:31], v[28:31], v[20:23], 0
	s_waitcnt vmcnt(4)
	v_mfma_f32_32x32x16_bf16 v[16:31], v[106:109], v[66:69], v[16:31]
	s_waitcnt vmcnt(3)
	v_mfma_f32_32x32x16_bf16 v[0:15], v[110:113], v[42:45], v[0:15]
	s_waitcnt vmcnt(0)
	v_mfma_f32_32x32x16_bf16 v[16:31], v[96:99], v[42:45], v[16:31]
	v_fma_f32 v42, v114, v50, -v34
	v_fma_f32 v43, v114, v51, -v35
	v_cvt_pk_bf16_f32 v34, v36, v37
	v_cvt_pk_bf16_f32 v35, v42, v43
	v_cvt_pk_bf16_f32 v36, v40, v41
	v_cvt_pk_bf16_f32 v37, v38, v39
	v_cndmask_b32_e32 v42, v226, v58, vcc
	v_lshlrev_b32_e32 v42, 2, v42
	s_waitcnt vmcnt(1)
	v_mfma_f32_32x32x16_bf16 v[0:15], v[100:103], v[34:37], v[0:15]
	v_lshl_add_u64 v[38:39], v[32:33], 0, v[178:179]
	v_lshlrev_b32_e32 v178, 1, v74
	v_lshl_add_u64 v[40:41], v[32:33], 0, v[178:179]
	s_waitcnt vmcnt(0)
	v_mfma_f32_32x32x16_bf16 v[16:31], v[46:49], v[34:37], v[16:31]
	s_nop 6
	v_cvt_pk_bf16_f32 v0, v0, v1
	v_cvt_pk_bf16_f32 v1, v2, v3
	v_cvt_pk_bf16_f32 v2, v4, v5
	v_cvt_pk_bf16_f32 v3, v6, v7
	v_cvt_pk_bf16_f32 v12, v12, v13
	v_cvt_pk_bf16_f32 v13, v14, v15
	v_cndmask_b32_e64 v4, v2, v0, s[4:5]
	v_cvt_pk_bf16_f32 v16, v16, v17
	v_cvt_pk_bf16_f32 v17, v18, v19
	v_cvt_pk_bf16_f32 v19, v22, v23
	v_cvt_pk_bf16_f32 v22, v24, v25
	v_cvt_pk_bf16_f32 v23, v26, v27
	v_cvt_pk_bf16_f32 v24, v28, v29
	v_cvt_pk_bf16_f32 v25, v30, v31
	v_cvt_pk_bf16_f32 v18, v20, v21
	v_cvt_pk_bf16_f32 v20, v8, v9
	v_cvt_pk_bf16_f32 v21, v10, v11
	v_cndmask_b32_e64 v5, v3, v1, s[4:5]
	v_cndmask_b32_e64 v10, v24, v22, s[4:5]
	v_cndmask_b32_e64 v11, v25, v23, s[4:5]
	v_cndmask_b32_e64 v6, v18, v16, s[4:5]
	v_cndmask_b32_e64 v7, v19, v17, s[4:5]
	v_cndmask_b32_e64 v8, v12, v20, s[4:5]
	v_cndmask_b32_e64 v9, v13, v21, s[4:5]
	ds_bpermute_b32 v4, v42, v4
	ds_bpermute_b32 v5, v42, v5
	ds_bpermute_b32 v28, v42, v10
	ds_bpermute_b32 v29, v42, v11
	ds_bpermute_b32 v14, v42, v6
	ds_bpermute_b32 v15, v42, v7
	ds_bpermute_b32 v26, v42, v8
	ds_bpermute_b32 v27, v42, v9
	s_waitcnt lgkmcnt(0)
	v_cndmask_b32_e64 v7, v5, v3, s[4:5]
	v_cndmask_b32_e64 v6, v4, v2, s[4:5]
	v_cndmask_b32_e64 v5, v1, v5, s[4:5]
	v_cndmask_b32_e64 v4, v0, v4, s[4:5]
	s_waitcnt lgkmcnt(4)
	v_cndmask_b32_e64 v3, v29, v25, s[4:5]
	v_cndmask_b32_e64 v2, v28, v24, s[4:5]
	v_cndmask_b32_e64 v1, v23, v29, s[4:5]
	v_cndmask_b32_e64 v0, v22, v28, s[4:5]
	s_waitcnt lgkmcnt(2)
	v_cndmask_b32_e64 v11, v15, v19, s[4:5]
	v_cndmask_b32_e64 v10, v14, v18, s[4:5]
	v_cndmask_b32_e64 v9, v17, v15, s[4:5]
	v_cndmask_b32_e64 v8, v16, v14, s[4:5]
	s_waitcnt lgkmcnt(0)
	v_cndmask_b32_e64 v15, v27, v13, s[4:5]
	v_cndmask_b32_e64 v14, v26, v12, s[4:5]
	v_cndmask_b32_e64 v13, v21, v27, s[4:5]
	v_cndmask_b32_e64 v12, v20, v26, s[4:5]
	global_store_dwordx4 v[38:39], v[4:7], off sc0 sc1
	global_store_dwordx4 v[38:39], v[8:11], off offset:64 sc0 sc1
	global_store_dwordx4 v[40:41], v[12:15], off sc0 sc1
